# adds: LN stats loads batched, ret_norm row prefetch, prologue conversions unrolled, pool-weight tile loads parallel, DA non-diagonal fast path, XA PV LDS read-ahead
# speedup vs baseline: 1.0120x; 1.0120x over previous
; DI void phase_prologue(const Params& p, char* lds) {
;     ...
;       if (jb.perm == 4) {
;         const int g = n >> 8, gk = k0 >> 8;
; #pragma unroll 8
;         for (int i = 0; i < 32; ++i) { int kl = kb + 4 * i; int k = k0 + kl; tile[kl * 129 + nl] = (g == gk) ? jb.src[(size_t)g * 65536 + (size_t)(k & 255) * 256 + (n & 255)] : 0.f; }
.LBB0_22:
	v_add_u32_e32 v145, s37, v142
	s_andn2_b64 vcc, exec, s[38:39]
	s_cbranch_vccnz .Lp4_zero
	s_load_dwordx2 s[50:51], s[34:35], 0x2b8
	v_mov_b32_e32 v75, v71
	s_waitcnt lgkmcnt(0)
	s_add_u32 s50, s50, s40
	s_addc_u32 s51, s51, s41
	v_and_b32_e32 v70, 0xff00, v145
	v_lshlrev_b32_e32 v70, 2, v70
	v_lshl_add_u64 v[148:149], s[50:51], 0, v[70:71]
	v_lshl_add_u64 v[148:149], v[148:149], 0, v[74:75]
	global_load_dword v150, v[148:149], off
	v_add_u32_e32 v70, 0x400, v145
	v_and_b32_e32 v70, 0xff00, v70
	v_lshlrev_b32_e32 v70, 2, v70
	v_lshl_add_u64 v[148:149], s[50:51], 0, v[70:71]
	v_lshl_add_u64 v[148:149], v[148:149], 0, v[74:75]
	global_load_dword v151, v[148:149], off
	v_add_u32_e32 v70, 0x800, v145
	v_and_b32_e32 v70, 0xff00, v70
	v_lshlrev_b32_e32 v70, 2, v70
	v_lshl_add_u64 v[148:149], s[50:51], 0, v[70:71]
	v_lshl_add_u64 v[148:149], v[148:149], 0, v[74:75]
	global_load_dword v152, v[148:149], off
	v_add_u32_e32 v70, 0xc00, v145
	v_and_b32_e32 v70, 0xff00, v70
	v_lshlrev_b32_e32 v70, 2, v70
	v_lshl_add_u64 v[148:149], s[50:51], 0, v[70:71]
	v_lshl_add_u64 v[148:149], v[148:149], 0, v[74:75]
	global_load_dword v153, v[148:149], off
	v_add_u32_e32 v70, 0x1000, v145
	v_and_b32_e32 v70, 0xff00, v70
	v_lshlrev_b32_e32 v70, 2, v70
	v_lshl_add_u64 v[148:149], s[50:51], 0, v[70:71]
	v_lshl_add_u64 v[148:149], v[148:149], 0, v[74:75]
	global_load_dword v154, v[148:149], off
	v_add_u32_e32 v70, 0x1400, v145
	v_and_b32_e32 v70, 0xff00, v70
	v_lshlrev_b32_e32 v70, 2, v70
	v_lshl_add_u64 v[148:149], s[50:51], 0, v[70:71]
	v_lshl_add_u64 v[148:149], v[148:149], 0, v[74:75]
	global_load_dword v155, v[148:149], off
	v_add_u32_e32 v70, 0x1800, v145
	v_and_b32_e32 v70, 0xff00, v70
	v_lshlrev_b32_e32 v70, 2, v70
	v_lshl_add_u64 v[148:149], s[50:51], 0, v[70:71]
	v_lshl_add_u64 v[148:149], v[148:149], 0, v[74:75]
	global_load_dword v156, v[148:149], off
	v_add_u32_e32 v70, 0x1c00, v145
	v_and_b32_e32 v70, 0xff00, v70
	v_lshlrev_b32_e32 v70, 2, v70
	v_lshl_add_u64 v[148:149], s[50:51], 0, v[70:71]
	v_lshl_add_u64 v[148:149], v[148:149], 0, v[74:75]
	global_load_dword v157, v[148:149], off
	s_waitcnt vmcnt(0)
	s_branch .Lp4_write
.Lp4_zero:
	v_mov_b32_e32 v150, 0
	v_mov_b32_e32 v151, 0
	v_mov_b32_e32 v152, 0
	v_mov_b32_e32 v153, 0
	v_mov_b32_e32 v154, 0
	v_mov_b32_e32 v155, 0
	v_mov_b32_e32 v156, 0
	v_mov_b32_e32 v157, 0
.Lp4_write:
	ds_write_b32 v144, v150
	ds_write_b32 v144, v151 offset:2064
	ds_write_b32 v144, v152 offset:4128
	ds_write_b32 v144, v153 offset:6192
	ds_write_b32 v144, v154 offset:8256
	ds_write_b32 v144, v155 offset:10320
	ds_write_b32 v144, v156 offset:12384
	ds_write_b32 v144, v157 offset:14448
	s_addk_i32 s37, 0x2000
	s_cmpk_eq_u32 s37, 0x8000
	v_add_u32_e32 v144, 0x4080, v144
	s_cbranch_scc0 .LBB0_22
	s_branch .LBB0_40

; DI unsigned pack2(float lo, float hi) { f32x2 v = {lo, hi}; bf2_t r = __builtin_convertvector(v, bf2_t); return __builtin_bit_cast(unsigned, r); }
; DI void phase_prologue(const Params& p, char* lds) {
;     ...
;   for (size_t li = (size_t)((int)blockIdx.x >> 3) * NT + tid; li < (size_t)S_ * D_ / 4 && (int)blockIdx.x < ((int)gridDim.x & ~7); li += (size_t)((int)gridDim.x >> 3) * NT) {
;     const size_t i = (size_t)(blockIdx.x & 7) * ((size_t)S_ * D_ / 4) + li;
;     f32x4 v = ((const f32x4*)p.x)[i];
;     u32x2 o; o.x = pack2(v[0], v[1]); o.y = pack2(v[2], v[3]); ((u32x2*)p.Xb)[i] = o;
;   }
.LBB0_55:
	global_load_dwordx4 v[10:13], v[4:5], off
	v_lshl_add_u64 v[4:5], v[4:5], 0, s[10:11]
	v_lshl_add_u64 v[8:9], v[8:9], 0, s[8:9]
	global_load_dwordx4 v[14:17], v[4:5], off
	v_lshl_add_u64 v[4:5], v[4:5], 0, s[10:11]
	v_lshl_add_u64 v[8:9], v[8:9], 0, s[8:9]
	global_load_dwordx4 v[18:21], v[4:5], off
	v_lshl_add_u64 v[4:5], v[4:5], 0, s[10:11]
	v_lshl_add_u64 v[8:9], v[8:9], 0, s[8:9]
	global_load_dwordx4 v[22:25], v[4:5], off
	v_lshl_add_u64 v[4:5], v[4:5], 0, s[10:11]
	v_lshl_add_u64 v[8:9], v[8:9], 0, s[8:9]
	global_load_dwordx4 v[26:29], v[4:5], off
	v_lshl_add_u64 v[4:5], v[4:5], 0, s[10:11]
	v_lshl_add_u64 v[8:9], v[8:9], 0, s[8:9]
	global_load_dwordx4 v[30:33], v[4:5], off
	v_lshl_add_u64 v[4:5], v[4:5], 0, s[10:11]
	v_lshl_add_u64 v[8:9], v[8:9], 0, s[8:9]
	global_load_dwordx4 v[34:37], v[4:5], off
	v_lshl_add_u64 v[4:5], v[4:5], 0, s[10:11]
	v_lshl_add_u64 v[8:9], v[8:9], 0, s[8:9]
	global_load_dwordx4 v[38:41], v[4:5], off
	v_lshl_add_u64 v[4:5], v[4:5], 0, s[10:11]
	v_lshl_add_u64 v[8:9], v[8:9], 0, s[8:9]
	s_waitcnt vmcnt(0)
	v_cvt_pk_bf16_f32 v10, v10, v11
	v_cvt_pk_bf16_f32 v11, v12, v13
	global_store_dwordx2 v[6:7], v[10:11], off
	v_lshl_add_u64 v[6:7], v[6:7], 0, s[12:13]
	v_cvt_pk_bf16_f32 v14, v14, v15
	v_cvt_pk_bf16_f32 v15, v16, v17
	global_store_dwordx2 v[6:7], v[14:15], off
	v_lshl_add_u64 v[6:7], v[6:7], 0, s[12:13]
	v_cvt_pk_bf16_f32 v18, v18, v19
	v_cvt_pk_bf16_f32 v19, v20, v21
	global_store_dwordx2 v[6:7], v[18:19], off
	v_lshl_add_u64 v[6:7], v[6:7], 0, s[12:13]
	v_cvt_pk_bf16_f32 v22, v22, v23
	v_cvt_pk_bf16_f32 v23, v24, v25
	global_store_dwordx2 v[6:7], v[22:23], off
	v_lshl_add_u64 v[6:7], v[6:7], 0, s[12:13]
	v_cvt_pk_bf16_f32 v26, v26, v27
	v_cvt_pk_bf16_f32 v27, v28, v29
	global_store_dwordx2 v[6:7], v[26:27], off
	v_lshl_add_u64 v[6:7], v[6:7], 0, s[12:13]
	v_cvt_pk_bf16_f32 v30, v30, v31
	v_cvt_pk_bf16_f32 v31, v32, v33
	global_store_dwordx2 v[6:7], v[30:31], off
	v_lshl_add_u64 v[6:7], v[6:7], 0, s[12:13]
	v_cvt_pk_bf16_f32 v34, v34, v35
	v_cvt_pk_bf16_f32 v35, v36, v37
	global_store_dwordx2 v[6:7], v[34:35], off
	v_lshl_add_u64 v[6:7], v[6:7], 0, s[12:13]
	v_cvt_pk_bf16_f32 v38, v38, v39
	v_cvt_pk_bf16_f32 v39, v40, v41
	global_store_dwordx2 v[6:7], v[38:39], off
	v_lshl_add_u64 v[6:7], v[6:7], 0, s[12:13]
	v_cmp_lt_u64_e32 vcc, s[36:37], v[8:9]
	s_or_b64 s[24:25], vcc, s[24:25]
	s_andn2_b64 exec, exec, s[24:25]
	s_cbranch_execnz .LBB0_55

; DI unsigned pack2(float lo, float hi) { f32x2 v = {lo, hi}; bf2_t r = __builtin_convertvector(v, bf2_t); return __builtin_bit_cast(unsigned, r); }
; DI void phase_prologue(const Params& p, char* lds) {
;     ...
;   for (size_t i = gtid; i < (size_t)2048 * D_ / 4; i += gsz) {
;     f32x4 v = ((const f32x4*)p.mem)[i];
;     u32x2 o; o.x = pack2(v[0], v[1]); o.y = pack2(v[2], v[3]); ((u32x2*)p.memb)[i] = o;
;   }
.LBB0_58:
	global_load_dwordx4 v[10:13], v[6:7], off
	v_lshl_add_u64 v[6:7], v[6:7], 0, s[10:11]
	v_lshl_add_u64 v[4:5], v[4:5], 0, s[8:9]
	global_load_dwordx4 v[14:17], v[6:7], off
	v_lshl_add_u64 v[6:7], v[6:7], 0, s[10:11]
	v_lshl_add_u64 v[4:5], v[4:5], 0, s[8:9]
	global_load_dwordx4 v[18:21], v[6:7], off
	v_lshl_add_u64 v[6:7], v[6:7], 0, s[10:11]
	v_lshl_add_u64 v[4:5], v[4:5], 0, s[8:9]
	global_load_dwordx4 v[22:25], v[6:7], off
	v_lshl_add_u64 v[6:7], v[6:7], 0, s[10:11]
	v_lshl_add_u64 v[4:5], v[4:5], 0, s[8:9]
	s_waitcnt vmcnt(0)
	v_cvt_pk_bf16_f32 v10, v10, v11
	v_cvt_pk_bf16_f32 v11, v12, v13
	global_store_dwordx2 v[8:9], v[10:11], off
	v_lshl_add_u64 v[8:9], v[8:9], 0, s[12:13]
	v_cvt_pk_bf16_f32 v14, v14, v15
	v_cvt_pk_bf16_f32 v15, v16, v17
	global_store_dwordx2 v[8:9], v[14:15], off
	v_lshl_add_u64 v[8:9], v[8:9], 0, s[12:13]
	v_cvt_pk_bf16_f32 v18, v18, v19
	v_cvt_pk_bf16_f32 v19, v20, v21
	global_store_dwordx2 v[8:9], v[18:19], off
	v_lshl_add_u64 v[8:9], v[8:9], 0, s[12:13]
	v_cvt_pk_bf16_f32 v22, v22, v23
	v_cvt_pk_bf16_f32 v23, v24, v25
	global_store_dwordx2 v[8:9], v[22:23], off
	v_lshl_add_u64 v[8:9], v[8:9], 0, s[12:13]
	v_cmp_lt_u64_e32 vcc, s[24:25], v[4:5]
	s_or_b64 s[14:15], vcc, s[14:15]
	s_andn2_b64 exec, exec, s[14:15]
	s_cbranch_execnz .LBB0_58

; DI u64_t ag_ld64(u64_t* p) { return __hip_atomic_load(p, __ATOMIC_RELAXED, __HIP_MEMORY_SCOPE_AGENT); }
;   DI void operator()(f32x16 (&acc)[2][4], int grow0, int gcol0, int lane, int w, char* lds) {
;     ...
;     if (tid < 256) {
;       float s1 = 0.f, s2 = 0.f;
; #pragma unroll
;       for (int q = 0; q < 4; ++q) { u64_t v = ag_ld64(myslots + tid * 4 + q); s1 += __uint_as_float((unsigned)v); s2 += __uint_as_float((unsigned)(v >> 32)); }
;       float mean = s1 * (1.f / 1024.f); float var = s2 * (1.f / 1024.f) - mean * mean; var = var < 0.f ? 0.f : var;
;       f32x2 sv = {mean, rsqrtf(var + LN_EPS)}; *(f32x2*)(stat + tid * 2) = sv;
;     }
.LBB0_256:
	s_or_b64 exec, exec, s[6:7]
	s_barrier
	s_and_saveexec_b64 s[6:7], s[40:41]
	s_cbranch_execz .LBB0_258
	v_lshl_add_u64 v[64:65], v[200:201], 3, v[64:65]
	global_load_dword v200, v[64:65], off sc1
	global_load_dword v201, v[64:65], off offset:4 sc1
	global_load_dword v5, v[64:65], off offset:8 sc1
	global_load_dword v7, v[64:65], off offset:12 sc1
	global_load_dword v9, v[64:65], off offset:16 sc1
	global_load_dword v11, v[64:65], off offset:20 sc1
	global_load_dword v13, v[64:65], off offset:24 sc1
	global_load_dword v15, v[64:65], off offset:28 sc1
	s_mov_b32 s2, 0x3a800000
	s_waitcnt vmcnt(0)
	v_add_f32_e32 v0, 0, v200
	v_add_f32_e32 v3, 0, v201
	v_add_f32_e32 v0, v0, v5
	v_add_f32_e32 v3, v3, v7
	v_add_f32_e32 v0, v0, v9
	v_add_f32_e32 v3, v3, v11
	v_add_f32_e32 v0, v0, v13
	v_mul_f32_e32 v64, 0x3a800000, v0
	v_add_f32_e32 v3, v3, v15
	v_mul_f32_e32 v0, v64, v64
	v_fma_f32 v0, v3, s2, -v0
	v_cmp_ngt_f32_e32 vcc, 0, v0
	s_mov_b32 s2, 0x800000
	s_nop 0
	v_cndmask_b32_e32 v0, 0, v0, vcc
	v_add_f32_e32 v0, 0x3727c5ac, v0
	v_cmp_gt_f32_e32 vcc, s2, v0
	v_mul_f32_e32 v3, 0x4b800000, v0
	s_nop 0
	v_cndmask_b32_e32 v0, v0, v3, vcc
	v_rsq_f32_e32 v0, v0
	s_nop 0
	v_mul_f32_e32 v3, 0x45800000, v0
	v_cndmask_b32_e32 v65, v0, v3, vcc
	v_lshlrev_b32_e32 v0, 3, v164
	ds_write_b64 v0, v[64:65]

; DI f32x16 mfma(bf16x8 a, bf16x8 b, f32x16 c) { return __builtin_amdgcn_mfma_f32_32x32x16_bf16(a, b, c, 0, 0, 0); }
; DI f32x16 zero16() { f32x16 z; for (int i = 0; i < 16; ++i) z[i] = 0.f; return z; }
; DI int launder(int x) { asm volatile("" : "+v"(x)); return x; }
; DI f32x16 dot16_lds(const char* img, int row, int hh, const bf16x8 (&qf)[16], f32x16 acc) {
;   const char* rp = img + row * 512; const int r15 = row & 15;
;   bf16x8 a[2][4];
; #pragma unroll
;   for (int q = 0; q < 4; ++q) a[0][q] = *(const bf16x8*)(rp + ((((q * 2) + hh) ^ r15) << 4));
; #pragma unroll
;   for (int g = 0; g < 4; ++g) {
;     if (g + 1 < 4) {
; #pragma unroll
;       for (int q = 0; q < 4; ++q) a[(g + 1) & 1][q] = *(const bf16x8*)(rp + (((((g + 1) * 4 + q) * 2 + hh) ^ r15) << 4));
;     }
; #pragma unroll
;     for (int q = 0; q < 4; ++q) acc = mfma(a[g & 1][q], qf[g * 4 + q], acc);
;     __builtin_amdgcn_sched_barrier(0);
;   }
;   return acc;
; }
; DI void phase_xa_attn(const Params& p, int layer, char* lds) {
;     ...
;       const int l31k = launder(l31);
; #pragma unroll
;       for (int mt = 0; mt < 2; ++mt) {
;         st[mt] = dot16_lds(kt_l, mt * 32 + l31k, hh, qf, zero16());
;       }
.LBB0_268:
	v_mov_b32_e32 v0, v164
	s_and_b32 s34, s3, 1
	v_or_b32_e32 v70, 2, v169
	v_lshlrev_b32_e32 v66, 9, v0
	v_bitop3_b32 v67, v0, v169, 15 bitop3:0x6c
	v_lshl_add_u32 v213, s34, 15, v66
	v_lshl_or_b32 v215, v67, 4, v213
	ds_read_b128 v[66:69], v215
	v_bitop3_b32 v70, v0, v70, 15 bitop3:0x6c
	v_or_b32_e32 v71, 4, v169
	v_bitop3_b32 v86, v0, v71, 15 bitop3:0x6c
	v_or_b32_e32 v71, 6, v169
	v_lshl_or_b32 v217, v70, 4, v213
	v_bitop3_b32 v90, v0, v71, 15 bitop3:0x6c
	v_or_b32_e32 v71, 8, v169
	ds_read_b128 v[82:85], v217
	v_bitop3_b32 v91, v0, v71, 15 bitop3:0x6c
	s_waitcnt lgkmcnt(0)
	v_mfma_f32_32x32x16_bf16 v[66:81], v[66:69], v[98:101], 0
	v_lshl_or_b32 v233, v86, 4, v213
	ds_read_b128 v[86:89], v233
	v_lshl_or_b32 v237, v90, 4, v213
	v_bitop3_b32 v94, v0, v196, 15 bitop3:0x6c
	v_bitop3_b32 v92, v0, v195, 15 bitop3:0x6c
	v_bitop3_b32 v95, v0, v197, 15 bitop3:0x6c
	v_lshl_or_b32 v238, v91, 4, v213
	v_mfma_f32_32x32x16_bf16 v[66:81], v[82:85], v[102:105], v[66:81]
	ds_read_b128 v[82:85], v237
	v_lshl_or_b32 v240, v94, 4, v213
	v_lshl_or_b32 v239, v92, 4, v213
	v_lshl_or_b32 v242, v95, 4, v213
	v_bitop3_b32 v219, v0, v198, 15 bitop3:0x6c
	v_bitop3_b32 v230, v0, v199, 15 bitop3:0x6c
	v_bitop3_b32 v231, v0, v200, 15 bitop3:0x6c
	s_waitcnt lgkmcnt(1)
	v_mfma_f32_32x32x16_bf16 v[66:81], v[86:89], v[106:109], v[66:81]
	ds_read_b128 v[86:89], v238
	ds_read_b128 v[90:93], v239
	ds_read_b128 v[94:97], v240
	ds_read_b128 v[226:229], v242
	v_bitop3_b32 v232, v0, v201, 15 bitop3:0x6c
	v_bitop3_b32 v234, v0, v202, 15 bitop3:0x6c
	v_bitop3_b32 v235, v0, v203, 15 bitop3:0x6c
	v_bitop3_b32 v236, v0, v204, 15 bitop3:0x6c
	v_bitop3_b32 v0, v0, v205, 15 bitop3:0x6c
	s_waitcnt lgkmcnt(4)
	v_mfma_f32_32x32x16_bf16 v[66:81], v[82:85], v[110:113], v[66:81]
	s_mul_i32 s3, s34, 0x8800
	s_waitcnt lgkmcnt(3)
	v_mfma_f32_32x32x16_bf16 v[66:81], v[86:89], v[114:117], v[66:81]
	v_lshl_or_b32 v219, v219, 4, v213
	v_lshl_or_b32 v247, v231, 4, v213
	v_lshl_or_b32 v246, v230, 4, v213
	ds_read_b128 v[82:85], v219
	ds_read_b128 v[86:89], v246
	v_lshl_or_b32 v248, v232, 4, v213
	s_waitcnt lgkmcnt(4)
	v_mfma_f32_32x32x16_bf16 v[66:81], v[90:93], v[118:121], v[66:81]
	s_waitcnt lgkmcnt(3)
	v_mfma_f32_32x32x16_bf16 v[66:81], v[94:97], v[122:125], v[66:81]
	ds_read_b128 v[90:93], v247
	ds_read_b128 v[94:97], v248
	s_waitcnt lgkmcnt(4)
	v_mfma_f32_32x32x16_bf16 v[66:81], v[226:229], v[126:129], v[66:81]
	s_waitcnt lgkmcnt(3)
	v_mfma_f32_32x32x16_bf16 v[66:81], v[82:85], v[130:133], v[66:81]
	v_lshl_or_b32 v249, v234, 4, v213
	v_lshl_or_b32 v251, v236, 4, v213
	v_lshl_or_b32 v250, v235, 4, v213
	v_lshl_or_b32 v0, v0, 4, v213
	s_waitcnt lgkmcnt(2)
	v_mfma_f32_32x32x16_bf16 v[66:81], v[86:89], v[134:137], v[66:81]
	ds_read_b128 v[82:85], v249
	ds_read_b128 v[86:89], v250
	s_waitcnt lgkmcnt(3)
	v_mfma_f32_32x32x16_bf16 v[66:81], v[90:93], v[138:141], v[66:81]
	ds_read_b128 v[90:93], v251
	ds_read_b128 v[226:229], v0
	s_waitcnt lgkmcnt(4)
	v_mfma_f32_32x32x16_bf16 v[66:81], v[94:97], v[142:145], v[66:81]
	s_waitcnt lgkmcnt(3)
	v_mfma_f32_32x32x16_bf16 v[66:81], v[82:85], v[146:149], v[66:81]
	s_waitcnt lgkmcnt(2)
	v_mfma_f32_32x32x16_bf16 v[66:81], v[86:89], v[150:153], v[66:81]
	s_waitcnt lgkmcnt(1)
	v_mfma_f32_32x32x16_bf16 v[66:81], v[90:93], v[154:157], v[66:81]
	s_waitcnt lgkmcnt(0)
	v_mfma_f32_32x32x16_bf16 v[66:81], v[226:229], v[158:161], v[66:81]
	ds_read_b128 v[82:85], v215 offset:16384
	ds_read_b128 v[226:229], v217 offset:16384
	s_waitcnt lgkmcnt(1)
	v_mfma_f32_32x32x16_bf16 v[82:97], v[82:85], v[98:101], 0
	s_waitcnt lgkmcnt(0)
	v_mfma_f32_32x32x16_bf16 v[82:97], v[226:229], v[102:105], v[82:97]
	ds_read_b128 v[226:229], v233 offset:16384
	ds_read_b128 v[230:233], v237 offset:16384
	s_waitcnt lgkmcnt(1)
	v_mfma_f32_32x32x16_bf16 v[82:97], v[226:229], v[106:109], v[82:97]
	ds_read_b128 v[226:229], v238 offset:16384
	ds_read_b128 v[234:237], v239 offset:16384
	ds_read_b128 v[238:241], v240 offset:16384
	ds_read_b128 v[242:245], v242 offset:16384
	s_waitcnt lgkmcnt(4)
	v_mfma_f32_32x32x16_bf16 v[82:97], v[230:233], v[110:113], v[82:97]
	s_waitcnt lgkmcnt(3)
	v_mfma_f32_32x32x16_bf16 v[82:97], v[226:229], v[114:117], v[82:97]
	s_waitcnt lgkmcnt(2)
	v_mfma_f32_32x32x16_bf16 v[82:97], v[234:237], v[118:121], v[82:97]
	s_waitcnt lgkmcnt(1)
	v_mfma_f32_32x32x16_bf16 v[82:97], v[238:241], v[122:125], v[82:97]
	ds_read_b128 v[226:229], v219 offset:16384
	ds_read_b128 v[230:233], v246 offset:16384
	ds_read_b128 v[234:237], v247 offset:16384
	ds_read_b128 v[238:241], v248 offset:16384
	s_waitcnt lgkmcnt(4)
	v_mfma_f32_32x32x16_bf16 v[82:97], v[242:245], v[126:129], v[82:97]
	s_waitcnt lgkmcnt(3)
	v_mfma_f32_32x32x16_bf16 v[82:97], v[226:229], v[130:133], v[82:97]
	s_waitcnt lgkmcnt(2)
	v_mfma_f32_32x32x16_bf16 v[82:97], v[230:233], v[134:137], v[82:97]
	s_waitcnt lgkmcnt(1)
	v_mfma_f32_32x32x16_bf16 v[82:97], v[234:237], v[138:141], v[82:97]
	ds_read_b128 v[226:229], v249 offset:16384
	ds_read_b128 v[230:233], v250 offset:16384
	ds_read_b128 v[234:237], v251 offset:16384
	ds_read_b128 v[242:245], v0 offset:16384
	s_waitcnt lgkmcnt(4)
	v_mfma_f32_32x32x16_bf16 v[82:97], v[238:241], v[142:145], v[82:97]
	s_waitcnt lgkmcnt(3)
	v_mfma_f32_32x32x16_bf16 v[82:97], v[226:229], v[146:149], v[82:97]
	s_waitcnt lgkmcnt(2)
	v_mfma_f32_32x32x16_bf16 v[82:97], v[230:233], v[150:153], v[82:97]
	s_waitcnt lgkmcnt(1)
	v_mfma_f32_32x32x16_bf16 v[82:97], v[234:237], v[154:157], v[82:97]
	s_waitcnt lgkmcnt(0)
; DI float ex2(float x) { return __builtin_amdgcn_exp2f(x); }
; template <int VSTR, bool DEFER = false>
; DI void softmax_pv(f32x16 (&st)[2], float& m, float& l, f32x16 (&o)[4], const char* vt, int erow0, int lane) {
;     ...
;   float mx = -1e30f;
; #pragma unroll
;   for (int mt = 0; mt < 2; ++mt)
; #pragma unroll
;     for (int i = 0; i < 16; ++i) mx = fmaxf(mx, st[mt][i]);
;   mx = xhalf_max(mx);
;   if (DEFER) {
;     constexpr float THR = 6.0f;
;     if (__any(mx > m + THR)) {
;       const float mn = fmaxf(m, mx);
;       const float al = ex2(m - mn);
;       m = mn;
;       l *= al;
; #pragma unroll
;       for (int et = 0; et < 4; ++et)
; #pragma unroll
;         for (int i = 0; i < 16; ++i) o[et][i] *= al;
;     }
;     float ps = 0.f;
; #pragma unroll
;     for (int mt = 0; mt < 2; ++mt)
; #pragma unroll
;       for (int i = 0; i < 16; ++i) { float pv = ex2(st[mt][i] - m); st[mt][i] = pv; ps += pv; }
;     l += ps;
;   } else {
;     const float mn = fmaxf(m, mx);
;     const float al = ex2(m - mn);
;     m = mn;
;     float ps = 0.f;
; #pragma unroll
;     for (int mt = 0; mt < 2; ++mt)
; #pragma unroll
;       for (int i = 0; i < 16; ++i) { float pv = ex2(st[mt][i] - mn); st[mt][i] = pv; ps += pv; }
;     l = l * al + ps;
; #pragma unroll
;     for (int et = 0; et < 4; ++et)
; #pragma unroll
;       for (int i = 0; i < 16; ++i) o[et][i] *= al;
;   }
; #pragma unroll
;   for (int mt = 0; mt < 2; ++mt)
; #pragma unroll
;     for (int s = 0; s < 2; ++s) {
;       u32x4 pb; pb.x = pack2(st[mt][8 * s], st[mt][8 * s + 1]); pb.y = pack2(st[mt][8 * s + 2], st[mt][8 * s + 3]);
;       pb.z = pack2(st[mt][8 * s + 4], st[mt][8 * s + 5]); pb.w = pack2(st[mt][8 * s + 6], st[mt][8 * s + 7]);
;       const bf16x8 bfrag = __builtin_bit_cast(bf16x8, pb);
;       const int kb = mt * 32 + 16 * s + 4 * hh;
; #pragma unroll
;       for (int et = 0; et < 4; ++et) {
;         const char* rp = vt + (erow0 + et * 32 + l31) * VSTR + kb * 2;
;         s16x4 lo = *(const s16x4*)rp, hi = *(const s16x4*)(rp + 16);
;         bf16x8 afrag = __builtin_shufflevector(lo, hi, 0, 1, 2, 3, 4, 5, 6, 7);
;         o[et] = mfma(afrag, bfrag, o[et]);
; DI void phase_xa_attn(const Params& p, int layer, char* lds) {
;     ...
; #pragma unroll
;       for (int mt = 0; mt < 2; ++mt)
; #pragma unroll
;         for (int i = 0; i < 16; ++i) st[mt][i] *= LOG2E;
	v_mfma_f32_32x32x16_bf16 v[82:97], v[242:245], v[158:161], v[82:97]
	v_mul_f32_e32 v0, 0x3fb8aa3b, v66
	v_mul_f32_e32 v213, 0x3fb8aa3b, v67
	v_mul_f32_e32 v215, 0x3fb8aa3b, v68
	v_mul_f32_e32 v217, 0x3fb8aa3b, v69
	v_max3_f32 v0, v0, s56, v213
	v_mul_f32_e32 v219, 0x3fb8aa3b, v70
	v_mul_f32_e32 v226, 0x3fb8aa3b, v71
	v_max3_f32 v0, v0, v215, v217
	v_mul_f32_e32 v227, 0x3fb8aa3b, v72
	v_mul_f32_e32 v228, 0x3fb8aa3b, v73
	v_max3_f32 v0, v0, v219, v226
	v_mul_f32_e32 v229, 0x3fb8aa3b, v74
	v_mul_f32_e32 v230, 0x3fb8aa3b, v75
	v_max3_f32 v0, v0, v227, v228
	v_mul_f32_e32 v231, 0x3fb8aa3b, v76
	v_mul_f32_e32 v232, 0x3fb8aa3b, v77
	v_max3_f32 v0, v0, v229, v230
	v_mul_f32_e32 v233, 0x3fb8aa3b, v78
	v_mul_f32_e32 v234, 0x3fb8aa3b, v79
	v_max3_f32 v0, v0, v231, v232
	v_mul_f32_e32 v235, 0x3fb8aa3b, v80
	v_mul_f32_e32 v236, 0x3fb8aa3b, v81
	v_max3_f32 v0, v0, v233, v234
	v_mul_f32_e32 v237, 0x3fb8aa3b, v82
	v_mul_f32_e32 v238, 0x3fb8aa3b, v83
	v_max3_f32 v0, v0, v235, v236
	v_mul_f32_e32 v239, 0x3fb8aa3b, v84
	v_mul_f32_e32 v240, 0x3fb8aa3b, v85
	v_max3_f32 v0, v0, v237, v238
	v_mul_f32_e32 v241, 0x3fb8aa3b, v86
	v_mul_f32_e32 v242, 0x3fb8aa3b, v87
	v_max3_f32 v0, v0, v239, v240
	v_mul_f32_e32 v243, 0x3fb8aa3b, v88
	v_mul_f32_e32 v244, 0x3fb8aa3b, v89
	v_max3_f32 v0, v0, v241, v242
	v_mul_f32_e32 v245, 0x3fb8aa3b, v90
	v_mul_f32_e32 v246, 0x3fb8aa3b, v91
	v_max3_f32 v0, v0, v243, v244
	v_mul_f32_e32 v247, 0x3fb8aa3b, v92
	v_mul_f32_e32 v248, 0x3fb8aa3b, v93
	v_max3_f32 v0, v0, v245, v246
	v_mul_f32_e32 v249, 0x3fb8aa3b, v94
	v_mul_f32_e32 v250, 0x3fb8aa3b, v95
	v_max3_f32 v0, v0, v247, v248
	v_mul_f32_e32 v251, 0x3fb8aa3b, v96
	v_mul_f32_e32 v252, 0x3fb8aa3b, v97
	v_max3_f32 v0, v0, v249, v250
	v_max3_f32 v0, v0, v251, v252
	v_mov_b32_e32 v213, v0
	s_nop 1
	v_permlane32_swap_b32_e32 v0, v213
	v_max3_f32 v213, v214, v0, v213
	v_fma_f32 v66, v66, s33, -v213
	v_sub_f32_e32 v0, v214, v213
	v_exp_f32_e32 v214, v66
	v_fma_f32 v66, v67, s33, -v213
	v_exp_f32_e32 v215, v66
	v_fma_f32 v66, v68, s33, -v213
	v_exp_f32_e32 v226, v66
	v_fma_f32 v66, v69, s33, -v213
	v_exp_f32_e32 v227, v66
	v_fma_f32 v66, v70, s33, -v213
	v_exp_f32_e32 v70, v66
	v_fma_f32 v66, v71, s33, -v213
	v_exp_f32_e32 v71, v66
	v_fma_f32 v66, v72, s33, -v213
	v_exp_f32_e32 v72, v66
	v_fma_f32 v66, v73, s33, -v213
	v_exp_f32_e32 v73, v66
	v_fma_f32 v66, v74, s33, -v213
	v_exp_f32_e32 v74, v66
	v_fma_f32 v66, v75, s33, -v213
	v_exp_f32_e32 v75, v66
	v_fma_f32 v66, v76, s33, -v213
	v_exp_f32_e32 v76, v66
	v_fma_f32 v66, v77, s33, -v213
	v_exp_f32_e32 v77, v66
	v_fma_f32 v66, v78, s33, -v213
	v_exp_f32_e32 v78, v66
	v_fma_f32 v66, v79, s33, -v213
	v_exp_f32_e32 v79, v66
	v_fma_f32 v66, v80, s33, -v213
	v_exp_f32_e32 v80, v66
	v_fma_f32 v66, v81, s33, -v213
	v_exp_f32_e32 v81, v66
	v_fma_f32 v66, v82, s33, -v213
	v_exp_f32_e32 v82, v66
	v_fma_f32 v66, v83, s33, -v213
	v_exp_f32_e32 v83, v66
	v_fma_f32 v66, v84, s33, -v213
	v_exp_f32_e32 v84, v66
	v_fma_f32 v66, v85, s33, -v213
	v_exp_f32_e32 v85, v66
	v_fma_f32 v66, v86, s33, -v213
	v_exp_f32_e32 v86, v66
	v_fma_f32 v66, v87, s33, -v213
	v_exp_f32_e32 v87, v66
	v_fma_f32 v66, v88, s33, -v213
	v_exp_f32_e32 v88, v66
	v_fma_f32 v66, v89, s33, -v213
	v_exp_f32_e32 v89, v66
	v_fma_f32 v66, v90, s33, -v213
	v_exp_f32_e32 v90, v66
	v_fma_f32 v66, v91, s33, -v213
	v_exp_f32_e32 v91, v66
	v_fma_f32 v66, v92, s33, -v213
	v_exp_f32_e32 v92, v66
	v_fma_f32 v66, v93, s33, -v213
	v_exp_f32_e32 v93, v66
	v_fma_f32 v66, v94, s33, -v213
	v_exp_f32_e32 v0, v0
	v_add_u32_e32 v217, s3, v206
	v_exp_f32_e32 v94, v66
	v_fma_f32 v66, v95, s33, -v213
	ds_read2_b64 v[228:231], v217 offset1:2
	ds_read2_b64 v[232:235], v217 offset0:4 offset1:6
	v_add_u32_e32 v219, 0x1000, v217
	v_add_u32_e32 v236, 0x2000, v217
	v_add_u32_e32 v237, 0x3000, v217
	ds_read2_b64 v[238:241], v219 offset0:32 offset1:34
	ds_read2_b64 v[242:245], v236 offset0:64 offset1:66
	ds_read2_b64 v[246:249], v237 offset0:96 offset1:98
	v_exp_f32_e32 v95, v66
	v_fma_f32 v66, v96, s33, -v213
	v_exp_f32_e32 v96, v66
	v_fma_f32 v66, v97, s33, -v213
	v_exp_f32_e32 v97, v66
	v_pk_mul_f32 v[64:65], v[64:65], v[0:1] op_sel_hi:[1,0]
	v_pk_mul_f32 v[62:63], v[62:63], v[0:1] op_sel_hi:[1,0]
	v_pk_mul_f32 v[60:61], v[60:61], v[0:1] op_sel_hi:[1,0]
	v_pk_mul_f32 v[58:59], v[58:59], v[0:1] op_sel_hi:[1,0]
	v_pk_mul_f32 v[56:57], v[56:57], v[0:1] op_sel_hi:[1,0]
	v_pk_mul_f32 v[54:55], v[54:55], v[0:1] op_sel_hi:[1,0]
	v_pk_mul_f32 v[52:53], v[52:53], v[0:1] op_sel_hi:[1,0]
	v_pk_mul_f32 v[50:51], v[50:51], v[0:1] op_sel_hi:[1,0]
	v_cvt_pk_bf16_f32 v66, v214, v215
	v_cvt_pk_bf16_f32 v67, v226, v227
	v_cvt_pk_bf16_f32 v68, v70, v71
	v_cvt_pk_bf16_f32 v69, v72, v73
	v_pk_mul_f32 v[48:49], v[48:49], v[0:1] op_sel_hi:[1,0]
	s_waitcnt lgkmcnt(4)
; DI unsigned pack2(float lo, float hi) { f32x2 v = {lo, hi}; bf2_t r = __builtin_convertvector(v, bf2_t); return __builtin_bit_cast(unsigned, r); }
; DI f32x16 mfma(bf16x8 a, bf16x8 b, f32x16 c) { return __builtin_amdgcn_mfma_f32_32x32x16_bf16(a, b, c, 0, 0, 0); }
; template <int VSTR, bool DEFER = false>
; DI void softmax_pv(f32x16 (&st)[2], float& m, float& l, f32x16 (&o)[4], const char* vt, int erow0, int lane) {
;     ...
; #pragma unroll
;     for (int et = 0; et < 4; ++et)
; #pragma unroll
;       for (int i = 0; i < 16; ++i) o[et][i] *= al;
;   }
; #pragma unroll
;   for (int mt = 0; mt < 2; ++mt)
; #pragma unroll
;     for (int s = 0; s < 2; ++s) {
;       u32x4 pb; pb.x = pack2(st[mt][8 * s], st[mt][8 * s + 1]); pb.y = pack2(st[mt][8 * s + 2], st[mt][8 * s + 3]);
;       pb.z = pack2(st[mt][8 * s + 4], st[mt][8 * s + 5]); pb.w = pack2(st[mt][8 * s + 6], st[mt][8 * s + 7]);
;       const bf16x8 bfrag = __builtin_bit_cast(bf16x8, pb);
;       const int kb = mt * 32 + 16 * s + 4 * hh;
; #pragma unroll
;       for (int et = 0; et < 4; ++et) {
;         const char* rp = vt + (erow0 + et * 32 + l31) * VSTR + kb * 2;
;         s16x4 lo = *(const s16x4*)rp, hi = *(const s16x4*)(rp + 16);
;         bf16x8 afrag = __builtin_shufflevector(lo, hi, 0, 1, 2, 3, 4, 5, 6, 7);
;         o[et] = mfma(afrag, bfrag, o[et]);
;       }
;     }
; DI void phase_xa_attn(const Params& p, int layer, char* lds) {
;     ...
;     auto vload = [&](int kt) {
; #pragma unroll
;       for (int i = 0; i < 4; ++i) { int idx = tid + i * NT; int row = idx >> 3, ch = idx & 7; rv[i] = *(const u32x4*)(Vt + ((size_t)(b * 4 + h) * 256 + row) * 256 + kt * 64 + ch * 8); }
;     };
;     auto vwrite = [&](int kt) {
;       char* vb_ = lds + 65536 + (kt & 1) * 34816;
; #pragma unroll
;       for (int i = 0; i < 4; ++i) { int idx = tid + i * NT; int row = idx >> 3, ch = idx & 7; char* d = vb_ + row * 136 + ch * 16; u32x2 a = {rv[i].x, rv[i].y}, bq = {rv[i].z, rv[i].w}; *(u32x2*)d = a; *(u32x2*)(d + 8) = bq; }
;     };
	v_mfma_f32_32x32x16_bf16 v[50:65], v[228:231], v[66:69], v[50:65]
	ds_read2_b64 v[228:231], v219 offset0:36 offset1:38
	v_mul_f32_e64 v46, v46, v0
	v_mul_f32_e64 v47, v47, v0
	v_mul_f32_e64 v44, v44, v0
	v_mul_f32_e64 v45, v45, v0
	v_pk_mul_f32 v[42:43], v[42:43], v[0:1] op_sel_hi:[1,0]
	v_pk_mul_f32 v[40:41], v[40:41], v[0:1] op_sel_hi:[1,0]
	v_pk_mul_f32 v[38:39], v[38:39], v[0:1] op_sel_hi:[1,0]
	v_pk_mul_f32 v[36:37], v[36:37], v[0:1] op_sel_hi:[1,0]
	v_pk_mul_f32 v[34:35], v[34:35], v[0:1] op_sel_hi:[1,0]
	v_pk_mul_f32 v[32:33], v[32:33], v[0:1] op_sel_hi:[1,0]
	s_waitcnt lgkmcnt(3)
	v_mfma_f32_32x32x16_bf16 v[34:49], v[238:241], v[66:69], v[34:49]
	ds_read2_b64 v[238:241], v236 offset0:68 offset1:70
	v_mul_f32_e64 v30, v30, v0
	v_mul_f32_e64 v31, v31, v0
	v_mul_f32_e64 v28, v28, v0
	v_mul_f32_e64 v29, v29, v0
	v_pk_mul_f32 v[26:27], v[26:27], v[0:1] op_sel_hi:[1,0]
	v_pk_mul_f32 v[24:25], v[24:25], v[0:1] op_sel_hi:[1,0]
	v_pk_mul_f32 v[22:23], v[22:23], v[0:1] op_sel_hi:[1,0]
	v_pk_mul_f32 v[20:21], v[20:21], v[0:1] op_sel_hi:[1,0]
	v_pk_mul_f32 v[18:19], v[18:19], v[0:1] op_sel_hi:[1,0]
	v_pk_mul_f32 v[16:17], v[16:17], v[0:1] op_sel_hi:[1,0]
	s_waitcnt lgkmcnt(3)
	v_mfma_f32_32x32x16_bf16 v[18:33], v[242:245], v[66:69], v[18:33]
	ds_read2_b64 v[242:245], v237 offset0:100 offset1:102
	v_mul_f32_e64 v14, v14, v0
	v_mul_f32_e64 v15, v15, v0
	v_mul_f32_e64 v12, v12, v0
	v_mul_f32_e64 v13, v13, v0
	v_pk_mul_f32 v[10:11], v[10:11], v[0:1] op_sel_hi:[1,0]
	v_pk_mul_f32 v[8:9], v[8:9], v[0:1] op_sel_hi:[1,0]
	v_pk_mul_f32 v[6:7], v[6:7], v[0:1] op_sel_hi:[1,0]
	v_pk_mul_f32 v[4:5], v[4:5], v[0:1] op_sel_hi:[1,0]
	v_pk_mul_f32 v[2:3], v[2:3], v[0:1] op_sel_hi:[1,0]
	s_andn2_b64 vcc, exec, s[6:7]
	s_waitcnt lgkmcnt(3)
	v_mfma_f32_32x32x16_bf16 v[2:17], v[246:249], v[66:69], v[2:17]
	ds_read2_b64 v[246:249], v217 offset0:8 offset1:10
	v_cvt_pk_bf16_f32 v66, v74, v75
	v_cvt_pk_bf16_f32 v67, v76, v77
	v_cvt_pk_bf16_f32 v68, v78, v79
	v_cvt_pk_bf16_f32 v69, v80, v81
	s_nop 0
	s_waitcnt lgkmcnt(3)
	v_mfma_f32_32x32x16_bf16 v[34:49], v[228:231], v[66:69], v[34:49]
	ds_read2_b64 v[228:231], v219 offset0:40 offset1:42
	s_waitcnt lgkmcnt(3)
	v_mfma_f32_32x32x16_bf16 v[18:33], v[238:241], v[66:69], v[18:33]
	ds_read2_b64 v[238:241], v236 offset0:72 offset1:74
	s_waitcnt lgkmcnt(3)
	v_mfma_f32_32x32x16_bf16 v[2:17], v[242:245], v[66:69], v[2:17]
	ds_read2_b64 v[242:245], v237 offset0:104 offset1:106
	s_waitcnt lgkmcnt(10)
	v_mfma_f32_32x32x16_bf16 v[50:65], v[232:235], v[66:69], v[50:65]
	ds_read2_b64 v[232:235], v217 offset0:12 offset1:14
	v_cvt_pk_bf16_f32 v66, v82, v83
	v_cvt_pk_bf16_f32 v67, v84, v85
	v_cvt_pk_bf16_f32 v68, v86, v87
	v_cvt_pk_bf16_f32 v69, v88, v89
	s_nop 0
	s_waitcnt lgkmcnt(4)
	v_mfma_f32_32x32x16_bf16 v[50:65], v[246:249], v[66:69], v[50:65]
	ds_read2_b64 v[246:249], v219 offset0:44 offset1:46
	s_waitcnt lgkmcnt(4)
	v_mfma_f32_32x32x16_bf16 v[34:49], v[228:231], v[66:69], v[34:49]
	ds_read2_b64 v[228:231], v236 offset0:76 offset1:78
	s_waitcnt lgkmcnt(4)
	v_mfma_f32_32x32x16_bf16 v[18:33], v[238:241], v[66:69], v[18:33]
	ds_read2_b64 v[238:241], v237 offset0:108 offset1:110
	s_waitcnt lgkmcnt(4)
	v_mfma_f32_32x32x16_bf16 v[2:17], v[242:245], v[66:69], v[2:17]
	v_cvt_pk_bf16_f32 v66, v90, v91
	v_cvt_pk_bf16_f32 v67, v92, v93
	v_cvt_pk_bf16_f32 v68, v94, v95
	v_cvt_pk_bf16_f32 v69, v96, v97
	s_nop 0
	s_waitcnt lgkmcnt(3)
	v_mfma_f32_32x32x16_bf16 v[50:65], v[232:235], v[66:69], v[50:65]
	s_waitcnt lgkmcnt(2)
	v_mfma_f32_32x32x16_bf16 v[34:49], v[246:249], v[66:69], v[34:49]
	s_waitcnt lgkmcnt(1)
	v_mfma_f32_32x32x16_bf16 v[18:33], v[228:231], v[66:69], v[18:33]
	s_waitcnt lgkmcnt(0)
	v_mfma_f32_32x32x16_bf16 v[2:17], v[238:241], v[66:69], v[2:17]
	s_cbranch_vccnz .LBB0_270
	s_lshl_b32 s92, s2, 7
	v_lshl_add_u64 v[66:67], v[182:183], 0, s[92:93]
	global_load_dwordx4 v[66:69], v[66:67], off
	v_lshl_add_u64 v[228:229], v[184:185], 0, s[92:93]
	global_load_dwordx4 v[228:231], v[228:229], off
	v_lshl_add_u64 v[232:233], v[186:187], 0, s[92:93]
	global_load_dwordx4 v[232:235], v[232:233], off
	v_lshl_add_u64 v[236:237], v[188:189], 0, s[92:93]
	global_load_dwordx4 v[236:239], v[236:237], off
	s_bitcmp1_b32 s2, 0
	s_mov_b32 s3, 0x18800
	s_cselect_b32 s3, s3, 0x10000
	v_add3_u32 v217, s3, v190, v191
	s_waitcnt vmcnt(3)
	ds_write2_b64 v217, v[66:67], v[68:69] offset1:1
	v_add3_u32 v66, s3, v192, v191
	s_waitcnt vmcnt(2)
	ds_write2_b64 v66, v[228:229], v[230:231] offset1:1
	v_add3_u32 v66, s3, v193, v191
	s_waitcnt vmcnt(1)
	ds_write2_b64 v66, v[232:233], v[234:235] offset1:1
	v_add3_u32 v66, s3, v194, v191
	s_waitcnt vmcnt(0)
	ds_write2_b64 v66, v[236:237], v[238:239] offset1:1

; DI u64_t ag_ld64(u64_t* p) { return __hip_atomic_load(p, __ATOMIC_RELAXED, __HIP_MEMORY_SCOPE_AGENT); }
;   DI void operator()(f32x16 (&acc)[2][4], int grow0, int gcol0, int lane, int w, char* lds) {
;     ...
;     if (tid < 256) {
;       float s1 = 0.f, s2 = 0.f;
; #pragma unroll
;       for (int q = 0; q < 4; ++q) { u64_t v = ag_ld64(myslots + tid * 4 + q); s1 += __uint_as_float((unsigned)v); s2 += __uint_as_float((unsigned)(v >> 32)); }
;       float mean = s1 * (1.f / 1024.f); float var = s2 * (1.f / 1024.f) - mean * mean; var = var < 0.f ? 0.f : var;
;       f32x2 sv = {mean, rsqrtf(var + LN_EPS)}; *(f32x2*)(stat + tid * 2) = sv;
;     }
.LBB0_373:
	s_or_b64 exec, exec, s[6:7]
	s_barrier
	s_and_saveexec_b64 s[6:7], s[40:41]
	s_cbranch_execz .LBB0_375
	v_lshl_add_u64 v[64:65], v[168:169], 3, v[64:65]
	global_load_dword v168, v[64:65], off sc1
	global_load_dword v169, v[64:65], off offset:4 sc1
	global_load_dword v21, v[64:65], off offset:8 sc1
	global_load_dword v23, v[64:65], off offset:12 sc1
	global_load_dword v25, v[64:65], off offset:16 sc1
	global_load_dword v27, v[64:65], off offset:20 sc1
	global_load_dword v29, v[64:65], off offset:24 sc1
	global_load_dword v31, v[64:65], off offset:28 sc1
	s_mov_b32 s2, 0x3a800000
	s_waitcnt vmcnt(0)
	v_add_f32_e32 v0, 0, v168
	v_add_f32_e32 v19, 0, v169
	v_add_f32_e32 v0, v0, v21
	v_add_f32_e32 v19, v19, v23
	v_add_f32_e32 v0, v0, v25
	v_add_f32_e32 v19, v19, v27
	v_add_f32_e32 v0, v0, v29
	v_mul_f32_e32 v64, 0x3a800000, v0
	v_add_f32_e32 v19, v19, v31
	v_mul_f32_e32 v0, v64, v64
	v_fma_f32 v0, v19, s2, -v0
	v_cmp_ngt_f32_e32 vcc, 0, v0
	s_mov_b32 s2, 0x800000
	s_nop 0
	v_cndmask_b32_e32 v0, 0, v0, vcc
	v_add_f32_e32 v0, 0x3727c5ac, v0
	v_cmp_gt_f32_e32 vcc, s2, v0
	v_mul_f32_e32 v19, 0x4b800000, v0
	s_nop 0
	v_cndmask_b32_e32 v0, v0, v19, vcc
	v_rsq_f32_e32 v0, v0
	s_nop 0
	v_mul_f32_e32 v19, 0x45800000, v0
	v_cndmask_b32_e32 v65, v0, v19, vcc
	v_lshlrev_b32_e32 v0, 3, v210
	ds_write_b64 v0, v[64:65]

; DI unsigned pack2(float lo, float hi) { f32x2 v = {lo, hi}; bf2_t r = __builtin_convertvector(v, bf2_t); return __builtin_bit_cast(unsigned, r); }
; DI void phase_ret_norm(const Params& p) {
;     ...
;   for (int lr = ((int)blockIdx.x >> 3) * 8 + w; lr < 8192 && (int)blockIdx.x < ((int)gridDim.x & ~7); lr += nxw) {
;     const int r = (blockIdx.x & 7) * 8192 + lr;
;     bf16_t* op = p.Or + (size_t)r * 512 + lane * 8;
;     const bf16_t* gp = p.G + (size_t)r * 512 + lane * 8;
;     u32x4 ov = *(const u32x4*)op, gv = *(const u32x4*)gp;
;     float o[8], g[8];
; #pragma unroll
;     for (int i = 0; i < 4; ++i) { o[2 * i] = __uint_as_float(ov[i] << 16); o[2 * i + 1] = __uint_as_float(ov[i] & 0xffff0000u); g[2 * i] = __uint_as_float(gv[i] << 16); g[2 * i + 1] = __uint_as_float(gv[i] & 0xffff0000u); }
;     float s = 0.f;
; #pragma unroll
;     for (int i = 0; i < 8; ++i) s += o[i];
; #pragma unroll
;     for (int of = 32; of > 0; of >>= 1) s += __shfl_xor(s, of);
;     const float mu = s * (1.f / 512.f);
;     float q = 0.f;
; #pragma unroll
;     for (int i = 0; i < 8; ++i) { float d = o[i] - mu; q += d * d; }
; #pragma unroll
;     for (int of = 32; of > 0; of >>= 1) q += __shfl_xor(q, of);
;     const float rs = rsqrtf(q * (1.f / 512.f) + LN_EPS);
;     u32x4 res;
; #pragma unroll
;     for (int i = 0; i < 4; ++i) {
;       float a = (o[2 * i] - mu) * rs * (g[2 * i] / (1.f + __expf(-g[2 * i])));
;       float b2 = (o[2 * i + 1] - mu) * rs * (g[2 * i + 1] / (1.f + __expf(-g[2 * i + 1])));
;       res[i] = pack2(a, b2);
;     }
.LBB0_407:
	s_cmp_lt_i32 s71, 1
	s_mov_b64 s[6:7], -1
	s_cbranch_scc1 .LBB0_431
	s_cmp_lg_u32 s71, 1
	s_cbranch_scc0 .LBB0_413
	v_mov_b32_e32 v10, v216
	v_readlane_b32 s2, v254, 34
	v_ashrrev_i32_e32 v2, 6, v10
	s_nop 0
	v_add_u32_e32 v0, s2, v2
	s_movk_i32 s2, 0x2000
	v_cmp_gt_i32_e32 vcc, s2, v0
	v_readlane_b32 s2, v253, 17
	v_readlane_b32 s3, v253, 18
	s_and_b64 s[2:3], vcc, s[2:3]
	s_and_saveexec_b64 s[40:41], s[2:3]
	s_load_dwordx4 s[44:47], s[0:1], 0xf0
	v_readlane_b32 s6, v254, 45
	v_readlane_b32 s7, v254, 46
	v_readlane_b32 s30, v254, 49
	v_readlane_b32 s31, v254, 50
	s_mov_b32 s7, 0x800000
	s_cbranch_execz .LBB0_412
	v_and_b32_e32 v3, 64, v222
	v_add_u32_e32 v3, 64, v3
	v_xor_b32_e32 v4, 32, v222
	v_cmp_lt_i32_e32 vcc, v4, v3
	v_xor_b32_e32 v5, 16, v222
	v_xor_b32_e32 v6, 8, v222
	v_cndmask_b32_e32 v4, v222, v4, vcc
	v_cmp_lt_i32_e32 vcc, v5, v3
	v_xor_b32_e32 v7, 4, v222
	v_xor_b32_e32 v8, 2, v222
	v_cndmask_b32_e32 v5, v222, v5, vcc
	v_cmp_lt_i32_e32 vcc, v6, v3
	v_xor_b32_e32 v9, 1, v222
	v_readlane_b32 s2, v254, 35
	v_cndmask_b32_e32 v6, v222, v6, vcc
	v_cmp_lt_i32_e32 vcc, v7, v3
	v_add_u32_e32 v2, s2, v2
	v_and_b32_e32 v10, 63, v10
	v_cndmask_b32_e32 v7, v222, v7, vcc
	v_cmp_lt_i32_e32 vcc, v8, v3
	v_lshlrev_b32_e32 v4, 2, v4
	v_lshlrev_b32_e32 v5, 2, v5
	v_cndmask_b32_e32 v8, v222, v8, vcc
	v_cmp_lt_i32_e32 vcc, v9, v3
	v_lshlrev_b32_e32 v6, 2, v6
	v_lshlrev_b32_e32 v7, 2, v7
	v_cndmask_b32_e32 v3, v222, v9, vcc
	v_lshlrev_b32_e32 v9, 2, v3
	v_ashrrev_i32_e32 v3, 31, v2
	v_lshlrev_b64 v[2:3], 10, v[2:3]
	v_lshlrev_b32_e32 v8, 2, v8
	v_lshl_or_b32 v2, v10, 4, v2
	s_mov_b64 s[42:43], 0
	s_waitcnt lgkmcnt(0)
	v_lshl_add_u64 v[44:45], s[46:47], 0, v[2:3]
	v_lshl_add_u64 v[46:47], s[44:45], 0, v[2:3]
	global_load_dwordx4 v[36:39], v[44:45], off
	global_load_dwordx4 v[40:43], v[46:47], off
	global_load_dword v48, v[44:45], off
	v_lshl_add_u64 v[2:3], v[2:3], 0, s[30:31]
.LBB0_411:
	s_waitcnt vmcnt(1)
	v_add_u32_e32 v0, s6, v0
	v_mov_b32_e32 v10, v36
	v_mov_b32_e32 v11, v37
	v_mov_b32_e32 v12, v38
	v_mov_b32_e32 v13, v39
	v_mov_b32_e32 v14, v40
	v_mov_b32_e32 v15, v41
	v_mov_b32_e32 v16, v42
	v_mov_b32_e32 v17, v43
	v_mov_b32_e32 v18, v44
	v_mov_b32_e32 v19, v45
	v_readfirstlane_b32 s2, v0
	s_cmp_gt_i32 s2, 0x1fff
	s_cbranch_scc1 .Lrn_nopf
	v_lshl_add_u64 v[44:45], s[46:47], 0, v[2:3]
	v_lshl_add_u64 v[46:47], s[44:45], 0, v[2:3]
	global_load_dwordx4 v[36:39], v[44:45], off
	global_load_dwordx4 v[40:43], v[46:47], off
	v_lshl_add_u64 v[2:3], v[2:3], 0, s[30:31]
.Lrn_nopf:
	v_lshlrev_b32_e32 v20, 16, v13
	v_lshlrev_b32_e32 v34, 16, v17
	v_and_b32_e32 v35, 0xffff0000, v17
	v_lshlrev_b32_e32 v17, 16, v16
	v_and_b32_e32 v16, 0xffff0000, v16
	v_and_b32_e32 v21, 0xffff0000, v13
	v_lshlrev_b32_e32 v22, 16, v12
	v_and_b32_e32 v23, 0xffff0000, v12
	v_mul_f32_e32 v12, 0xbfb8aa3b, v17
	v_mul_f32_e32 v13, 0xbfb8aa3b, v16
	v_exp_f32_e32 v12, v12
	v_exp_f32_e32 v13, v13
	s_nop 0
	v_pk_add_f32 v[12:13], v[12:13], 1.0 op_sel_hi:[1,0]
	s_nop 0
	v_div_scale_f32 v24, s[2:3], v13, v13, v16
	v_rcp_f32_e32 v25, v24
	s_nop 0
	v_fma_f32 v26, -v24, v25, 1.0
	v_fmac_f32_e32 v25, v26, v25
	v_div_scale_f32 v26, vcc, v16, v13, v16
	v_mul_f32_e32 v27, v26, v25
	v_fma_f32 v28, -v24, v27, v26
	v_fmac_f32_e32 v27, v28, v25
	v_fma_f32 v24, -v24, v27, v26
	v_div_fmas_f32 v24, v24, v25, v27
	v_div_fixup_f32 v13, v24, v13, v16
	v_div_scale_f32 v16, s[2:3], v12, v12, v17
	v_rcp_f32_e32 v24, v16
	s_nop 0
	v_fma_f32 v25, -v16, v24, 1.0
	v_fmac_f32_e32 v24, v25, v24
	v_div_scale_f32 v25, vcc, v17, v12, v17
	v_mul_f32_e32 v26, v25, v24
	v_fma_f32 v27, -v16, v26, v25
	v_fmac_f32_e32 v26, v27, v24
	v_fma_f32 v16, -v16, v26, v25
	v_div_fmas_f32 v16, v16, v24, v26
	v_div_fixup_f32 v12, v16, v12, v17
	v_lshlrev_b32_e32 v16, 16, v11
	v_and_b32_e32 v17, 0xffff0000, v11
	v_lshlrev_b32_e32 v11, 16, v15
	v_and_b32_e32 v15, 0xffff0000, v15
	v_mul_f32_e32 v24, 0xbfb8aa3b, v11
	v_mul_f32_e32 v25, 0xbfb8aa3b, v15
	v_exp_f32_e32 v24, v24
	v_exp_f32_e32 v25, v25
	s_nop 0
	v_pk_add_f32 v[24:25], v[24:25], 1.0 op_sel_hi:[1,0]
	s_nop 0
	v_div_scale_f32 v26, s[2:3], v25, v25, v15
	v_rcp_f32_e32 v27, v26
	s_nop 0
	v_fma_f32 v28, -v26, v27, 1.0
	v_fmac_f32_e32 v27, v28, v27
	v_div_scale_f32 v28, vcc, v15, v25, v15
	v_mul_f32_e32 v29, v28, v27
	v_fma_f32 v30, -v26, v29, v28
	v_fmac_f32_e32 v29, v30, v27
	v_fma_f32 v26, -v26, v29, v28
	v_div_fmas_f32 v26, v26, v27, v29
	v_div_fixup_f32 v25, v26, v25, v15
	v_div_scale_f32 v15, s[2:3], v24, v24, v11
	v_rcp_f32_e32 v26, v15
	s_nop 0
	v_fma_f32 v27, -v15, v26, 1.0
	v_fmac_f32_e32 v26, v27, v26
	v_div_scale_f32 v27, vcc, v11, v24, v11
	v_mul_f32_e32 v28, v27, v26
	v_fma_f32 v29, -v15, v28, v27
	v_fmac_f32_e32 v28, v29, v26
	v_fma_f32 v15, -v15, v28, v27
	v_div_fmas_f32 v15, v15, v26, v28
	v_lshlrev_b32_e32 v26, 16, v10
	v_div_fixup_f32 v24, v15, v24, v11
	v_and_b32_e32 v27, 0xffff0000, v10
	v_lshlrev_b32_e32 v15, 16, v14
	v_and_b32_e32 v14, 0xffff0000, v14
	v_add_f32_e32 v10, 0, v26
	v_add_f32_e32 v28, v10, v27
	v_mul_f32_e32 v10, 0xbfb8aa3b, v15
	v_mul_f32_e32 v11, 0xbfb8aa3b, v14
	v_exp_f32_e32 v10, v10
	v_exp_f32_e32 v11, v11
	s_nop 0
	v_pk_add_f32 v[10:11], v[10:11], 1.0 op_sel_hi:[1,0]
	s_nop 0
	v_div_scale_f32 v29, s[2:3], v11, v11, v14
	v_rcp_f32_e32 v30, v29
	s_nop 0
	v_fma_f32 v31, -v29, v30, 1.0
	v_fmac_f32_e32 v30, v31, v30
	v_div_scale_f32 v31, vcc, v14, v11, v14
	v_mul_f32_e32 v32, v31, v30
	v_fma_f32 v33, -v29, v32, v31
	v_fmac_f32_e32 v32, v33, v30
	v_fma_f32 v29, -v29, v32, v31
	v_div_fmas_f32 v29, v29, v30, v32
	v_div_fixup_f32 v11, v29, v11, v14
	v_div_scale_f32 v14, s[2:3], v10, v10, v15
	v_rcp_f32_e32 v29, v14
	s_nop 0
	v_fma_f32 v30, -v14, v29, 1.0
	v_fmac_f32_e32 v29, v30, v29
	v_div_scale_f32 v30, vcc, v15, v10, v15
	v_mul_f32_e32 v31, v30, v29
	v_fma_f32 v32, -v14, v31, v30
	v_fmac_f32_e32 v31, v32, v29
	v_fma_f32 v14, -v14, v31, v30
	v_div_fmas_f32 v14, v14, v29, v31
	v_div_fixup_f32 v10, v14, v10, v15
	v_add_f32_e32 v14, v28, v16
	v_add_f32_e32 v14, v14, v17
	v_add_f32_e32 v14, v14, v22
	v_add_f32_e32 v14, v14, v23
	v_add_f32_e32 v14, v14, v20
	v_add_f32_e32 v14, v14, v21
	ds_bpermute_b32 v15, v4, v14
	s_waitcnt lgkmcnt(0)
; DI unsigned pack2(float lo, float hi) { f32x2 v = {lo, hi}; bf2_t r = __builtin_convertvector(v, bf2_t); return __builtin_bit_cast(unsigned, r); }
; DI void phase_ret_norm(const Params& p) {
;     ...
;     float s = 0.f;
; #pragma unroll
;     for (int i = 0; i < 8; ++i) s += o[i];
; #pragma unroll
;     for (int of = 32; of > 0; of >>= 1) s += __shfl_xor(s, of);
;     const float mu = s * (1.f / 512.f);
;     float q = 0.f;
; #pragma unroll
;     for (int i = 0; i < 8; ++i) { float d = o[i] - mu; q += d * d; }
; #pragma unroll
;     for (int of = 32; of > 0; of >>= 1) q += __shfl_xor(q, of);
;     const float rs = rsqrtf(q * (1.f / 512.f) + LN_EPS);
;     u32x4 res;
; #pragma unroll
;     for (int i = 0; i < 4; ++i) {
;       float a = (o[2 * i] - mu) * rs * (g[2 * i] / (1.f + __expf(-g[2 * i])));
;       float b2 = (o[2 * i + 1] - mu) * rs * (g[2 * i + 1] / (1.f + __expf(-g[2 * i + 1])));
;       res[i] = pack2(a, b2);
;     }
;     *(u32x4*)op = res;
	v_add_f32_e32 v14, v14, v15
	ds_bpermute_b32 v15, v5, v14
	s_waitcnt lgkmcnt(0)
	v_add_f32_e32 v14, v14, v15
	ds_bpermute_b32 v15, v6, v14
	s_waitcnt lgkmcnt(0)
	v_add_f32_e32 v14, v14, v15
	ds_bpermute_b32 v15, v7, v14
	s_waitcnt lgkmcnt(0)
	v_add_f32_e32 v14, v14, v15
	ds_bpermute_b32 v15, v8, v14
	s_waitcnt lgkmcnt(0)
	v_add_f32_e32 v14, v14, v15
	ds_bpermute_b32 v15, v9, v14
	s_waitcnt lgkmcnt(0)
	v_add_f32_e32 v14, v14, v15
	v_mul_f32_e32 v14, 0x3b000000, v14
	v_pk_add_f32 v[26:27], v[26:27], v[14:15] op_sel_hi:[1,0] neg_lo:[0,1] neg_hi:[0,1]
	v_pk_add_f32 v[16:17], v[16:17], v[14:15] op_sel_hi:[1,0] neg_lo:[0,1] neg_hi:[0,1]
	v_pk_mul_f32 v[28:29], v[26:27], v[26:27]
	v_pk_mul_f32 v[30:31], v[16:17], v[16:17]
	v_add_f32_e32 v28, v28, v29
	v_pk_add_f32 v[22:23], v[22:23], v[14:15] op_sel_hi:[1,0] neg_lo:[0,1] neg_hi:[0,1]
	v_add_f32_e32 v28, v30, v28
	v_pk_mul_f32 v[32:33], v[22:23], v[22:23]
	v_add_f32_e32 v28, v31, v28
	v_pk_add_f32 v[14:15], v[20:21], v[14:15] op_sel_hi:[1,0] neg_lo:[0,1] neg_hi:[0,1]
	v_add_f32_e32 v28, v32, v28
	v_pk_mul_f32 v[20:21], v[14:15], v[14:15]
	v_add_f32_e32 v28, v33, v28
	v_add_f32_e32 v20, v20, v28
	v_add_f32_e32 v20, v21, v20
	ds_bpermute_b32 v21, v4, v20
	s_waitcnt lgkmcnt(0)
	v_add_f32_e32 v20, v20, v21
	ds_bpermute_b32 v21, v5, v20
	s_waitcnt lgkmcnt(0)
	v_add_f32_e32 v20, v20, v21
	ds_bpermute_b32 v21, v6, v20
	s_waitcnt lgkmcnt(0)
	v_add_f32_e32 v20, v20, v21
	ds_bpermute_b32 v21, v7, v20
	s_waitcnt lgkmcnt(0)
	v_add_f32_e32 v20, v20, v21
	ds_bpermute_b32 v21, v8, v20
	s_waitcnt lgkmcnt(0)
	v_add_f32_e32 v20, v20, v21
	ds_bpermute_b32 v21, v9, v20
	s_waitcnt lgkmcnt(0)
	v_add_f32_e32 v20, v20, v21
	v_fmamk_f32 v20, v20, 0x3b000000, v218
	v_cmp_gt_f32_e32 vcc, s7, v20
	v_mul_f32_e32 v21, 0x4b800000, v20
	s_nop 0
	v_cndmask_b32_e32 v20, v20, v21, vcc
	v_rsq_f32_e32 v20, v20
	s_nop 0
	v_mul_f32_e32 v21, 0x45800000, v20
	v_cndmask_b32_e32 v20, v20, v21, vcc
	v_pk_mul_f32 v[26:27], v[26:27], v[20:21] op_sel_hi:[1,0]
	v_pk_mul_f32 v[16:17], v[16:17], v[20:21] op_sel_hi:[1,0]
	v_pk_mul_f32 v[10:11], v[10:11], v[26:27]
	v_pk_mul_f32 v[16:17], v[24:25], v[16:17]
	v_cvt_pk_bf16_f32 v10, v10, v11
	v_cvt_pk_bf16_f32 v11, v16, v17
	v_pk_mul_f32 v[16:17], v[22:23], v[20:21] op_sel_hi:[1,0]
	v_pk_mul_f32 v[14:15], v[14:15], v[20:21] op_sel_hi:[1,0]
	v_pk_mul_f32 v[12:13], v[12:13], v[16:17]
	s_nop 0
	v_cvt_pk_bf16_f32 v12, v12, v13
	v_mul_f32_e32 v13, 0xbfb8aa3b, v34
	v_exp_f32_e32 v16, v13
	v_mul_f32_e32 v13, 0xbfb8aa3b, v35
	v_exp_f32_e32 v17, v13
	s_nop 0
	v_pk_add_f32 v[16:17], v[16:17], 1.0 op_sel_hi:[1,0]
	s_nop 0
	v_div_scale_f32 v13, s[2:3], v17, v17, v35
	v_rcp_f32_e32 v20, v13
	s_nop 0
	v_fma_f32 v21, -v13, v20, 1.0
	v_fmac_f32_e32 v20, v21, v20
	v_div_scale_f32 v21, vcc, v35, v17, v35
	v_mul_f32_e32 v22, v21, v20
	v_fma_f32 v23, -v13, v22, v21
	v_fmac_f32_e32 v22, v23, v20
	v_fma_f32 v13, -v13, v22, v21
	v_div_fmas_f32 v13, v13, v20, v22
	v_div_fixup_f32 v17, v13, v17, v35
	v_div_scale_f32 v13, s[2:3], v16, v16, v34
	v_rcp_f32_e32 v20, v13
	s_movk_i32 s2, 0x1fff
	v_fma_f32 v21, -v13, v20, 1.0
	v_fmac_f32_e32 v20, v21, v20
	v_div_scale_f32 v21, vcc, v34, v16, v34
	v_mul_f32_e32 v22, v21, v20
	v_fma_f32 v23, -v13, v22, v21
	v_fmac_f32_e32 v22, v23, v20
	v_fma_f32 v13, -v13, v22, v21
	v_div_fmas_f32 v13, v13, v20, v22
	v_div_fixup_f32 v16, v13, v16, v34
	v_pk_mul_f32 v[14:15], v[16:17], v[14:15]
	v_cmp_lt_i32_e32 vcc, s2, v0
	v_cvt_pk_bf16_f32 v13, v14, v15
	s_or_b64 s[42:43], vcc, s[42:43]
	global_store_dwordx4 v[18:19], v[10:13], off
	s_andn2_b64 exec, exec, s[42:43]
	s_cbranch_execnz .LBB0_411

; DI int crow(int i, int hh) { return (i & 3) + 8 * (i >> 2) + 4 * hh; }
; DI f32x16 mfma(bf16x8 a, bf16x8 b, f32x16 c) { return __builtin_amdgcn_mfma_f32_32x32x16_bf16(a, b, c, 0, 0, 0); }
; DI f32x16 zero16() { f32x16 z; for (int i = 0; i < 16; ++i) z[i] = 0.f; return z; }
; DI void phase_da_attn(const Params& p, int j, char* lds) {
;     ...
;       if (kt * 64 <= q0 + 31) {
;         f32x16 st[2];
; #pragma unroll
;         for (int mt = 0; mt < 2; ++mt) {
;           st[mt] = zero16();
;           const int row = mt * 32 + l31;
; #pragma unroll
;           for (int kk = 0; kk < 4; ++kk) {
;             int ch = c * 8 + kk * 2 + hh;
;             bf16x8 a = *(const bf16x8*)(kt_l + row * 256 + ((ch ^ (row & 15)) << 4));
;             st[mt] = mfma(a, qf[kk], st[mt]);
;           }
;         }
;         const bool diag = kt * 64 + 63 > q0;
; #pragma unroll
;         for (int mt = 0; mt < 2; ++mt)
; #pragma unroll
;           for (int i = 0; i < 16; ++i) {
;             float s = st[mt][i] * sc;
;             if (diag) { int key = kt * 64 + mt * 32 + crow(i, hh); if (key > myq) s = -1e30f; }
;             st[mt][i] = s;
;           }
.LBB0_497:
	s_add_i32 s7, s6, 0xffffff80
	v_cmp_le_i32_e32 vcc, s7, v151
	s_and_saveexec_b64 s[30:31], vcc
	s_cbranch_execz .LBB0_501
	s_bitcmp1_b32 s44, 0
	s_cselect_b32 s7, 0x8400, 0
	v_add_u32_e32 v70, s7, v176
	v_add_u32_e32 v71, v70, v182
	s_add_i32 s101, s6, 0xffffffbf
	v_cmp_gt_i32_e32 vcc, s101, v187
	s_cbranch_vccz .Lda_fast
	ds_read_b128 v[66:69], v71
	v_add_u32_e32 v155, v70, v183
	ds_read_b128 v[188:191], v155 offset:8192
	v_add_u32_e32 v192, v70, v184
	v_add_u32_e32 v193, v70, v185
	v_add_u32_e32 v197, s6, v142
	s_add_i32 s44, s6, 0xffffffbf
	v_cmp_gt_i32_e32 vcc, s44, v187
	s_waitcnt lgkmcnt(1)
	v_mfma_f32_32x32x16_bf16 v[82:97], v[66:69], v[110:113], 0
	ds_read_b128 v[66:69], v155
	v_add_u32_e32 v155, 0xffffff80, v197
	v_cmp_gt_i32_e64 s[44:45], v155, v154
	s_and_b64 s[44:45], vcc, s[44:45]
	s_waitcnt lgkmcnt(0)
	v_mfma_f32_32x32x16_bf16 v[82:97], v[66:69], v[106:109], v[82:97]
	ds_read_b128 v[66:69], v192
	s_waitcnt lgkmcnt(0)
	v_mfma_f32_32x32x16_bf16 v[82:97], v[66:69], v[102:105], v[82:97]
	ds_read_b128 v[66:69], v193
	s_waitcnt lgkmcnt(0)
	v_mfma_f32_32x32x16_bf16 v[82:97], v[66:69], v[98:101], v[82:97]
	ds_read_b128 v[66:69], v71 offset:8192
	s_waitcnt lgkmcnt(0)
	v_mfma_f32_32x32x16_bf16 v[66:81], v[66:69], v[110:113], 0
	s_nop 8
	v_mul_f32_e32 v82, 0x3e38aa3b, v82
	v_cndmask_b32_e64 v82, v82, v225, s[44:45]
	v_mul_f32_e32 v83, 0x3e38aa3b, v83
	v_cmp_lt_i32_e64 s[44:45], v155, v154
	v_mul_f32_e32 v84, 0x3e38aa3b, v84
	s_nop 0
	v_cndmask_b32_e64 v155, v225, v83, s[44:45]
	v_mfma_f32_32x32x16_bf16 v[66:81], v[188:191], v[106:109], v[66:81]
	ds_read_b128 v[188:191], v192 offset:8192
	v_cndmask_b32_e32 v83, v83, v155, vcc
	v_add_u32_e32 v155, 0xffffff82, v197
	v_cmp_gt_i32_e64 s[44:45], v155, v154
	s_and_b64 s[44:45], vcc, s[44:45]
	s_nop 0
	v_cndmask_b32_e64 v155, v84, v225, s[44:45]
	s_waitcnt lgkmcnt(0)
	v_mfma_f32_32x32x16_bf16 v[66:81], v[188:191], v[102:105], v[66:81]
	ds_read_b128 v[188:191], v193 offset:8192
	v_mul_f32_e32 v84, 0x3e38aa3b, v85
	v_add_u32_e32 v85, 0xffffff83, v197
	v_cmp_gt_i32_e64 s[44:45], v85, v154
	s_and_b64 s[44:45], vcc, s[44:45]
	v_add_u32_e32 v85, 0xffffff88, v197
	s_waitcnt lgkmcnt(0)
	v_mfma_f32_32x32x16_bf16 v[66:81], v[188:191], v[98:101], v[66:81]
	v_cndmask_b32_e64 v188, v84, v225, s[44:45]
	v_cmp_gt_i32_e64 s[44:45], v85, v154
	v_mul_f32_e32 v84, 0x3e38aa3b, v86
	s_and_b64 s[44:45], vcc, s[44:45]
	v_add_u32_e32 v85, 0xffffff89, v197
	v_cndmask_b32_e64 v193, v84, v225, s[44:45]
	v_cmp_gt_i32_e64 s[44:45], v85, v154
	v_mul_f32_e32 v84, 0x3e38aa3b, v87
	s_and_b64 s[44:45], vcc, s[44:45]
	v_add_u32_e32 v85, 0xffffff8a, v197
	v_cndmask_b32_e64 v194, v84, v225, s[44:45]
	v_cmp_gt_i32_e64 s[44:45], v85, v154
	v_mul_f32_e32 v84, 0x3e38aa3b, v88
	s_and_b64 s[44:45], vcc, s[44:45]
	v_add_u32_e32 v85, 0xffffff8b, v197
	v_cndmask_b32_e64 v195, v84, v225, s[44:45]
	v_cmp_gt_i32_e64 s[44:45], v85, v154
	v_mul_f32_e32 v84, 0x3e38aa3b, v89
	s_and_b64 s[44:45], vcc, s[44:45]
	v_add_u32_e32 v85, 0xffffff90, v197
	v_cndmask_b32_e64 v196, v84, v225, s[44:45]
	v_cmp_gt_i32_e64 s[44:45], v85, v154
	v_mul_f32_e32 v84, 0x3e38aa3b, v90
	s_and_b64 s[44:45], vcc, s[44:45]
	v_add_u32_e32 v85, 0xffffff91, v197
	v_cndmask_b32_e64 v191, v84, v225, s[44:45]
	v_cmp_gt_i32_e64 s[44:45], v85, v154
	v_mul_f32_e32 v84, 0x3e38aa3b, v91
	s_and_b64 s[44:45], vcc, s[44:45]
	v_add_u32_e32 v85, 0xffffff92, v197
	v_cndmask_b32_e64 v192, v84, v225, s[44:45]
	v_cmp_gt_i32_e64 s[44:45], v85, v154
	v_mul_f32_e32 v84, 0x3e38aa3b, v92
	s_and_b64 s[44:45], vcc, s[44:45]
	v_add_u32_e32 v85, 0xffffff93, v197
	v_cndmask_b32_e64 v189, v84, v225, s[44:45]
	v_cmp_gt_i32_e64 s[44:45], v85, v154
	v_mul_f32_e32 v84, 0x3e38aa3b, v93
	s_and_b64 s[44:45], vcc, s[44:45]
	v_add_u32_e32 v85, 0xffffff98, v197
	v_cndmask_b32_e64 v190, v84, v225, s[44:45]
	v_cmp_gt_i32_e64 s[44:45], v85, v154
	v_mul_f32_e32 v84, 0x3e38aa3b, v94
	s_and_b64 s[44:45], vcc, s[44:45]
	v_add_u32_e32 v85, 0xffffff99, v197
	v_cndmask_b32_e64 v93, v84, v225, s[44:45]
	v_cmp_gt_i32_e64 s[44:45], v85, v154
	v_mul_f32_e32 v84, 0x3e38aa3b, v95
	s_and_b64 s[44:45], vcc, s[44:45]
	v_add_u32_e32 v85, 0xffffff9a, v197
	v_cndmask_b32_e64 v94, v84, v225, s[44:45]
	v_cmp_gt_i32_e64 s[44:45], v85, v154
	v_mul_f32_e32 v84, 0x3e38aa3b, v96
	s_and_b64 s[44:45], vcc, s[44:45]
	v_add_u32_e32 v85, 0xffffff9b, v197
	v_cndmask_b32_e64 v95, v84, v225, s[44:45]
	v_cmp_gt_i32_e64 s[44:45], v85, v154
	v_mul_f32_e32 v84, 0x3e38aa3b, v97
	s_and_b64 s[44:45], vcc, s[44:45]
	v_cndmask_b32_e64 v92, v84, v225, s[44:45]
	v_add_u32_e32 v84, 0xffffffa0, v197
	v_cmp_gt_i32_e64 s[44:45], v84, v154
	v_mul_f32_e32 v66, 0x3e38aa3b, v66
	s_and_b64 s[44:45], vcc, s[44:45]
	v_cndmask_b32_e64 v89, v66, v225, s[44:45]
	v_mul_f32_e32 v66, 0x3e38aa3b, v67
	v_add_u32_e32 v67, 0xffffffa1, v197
	v_cmp_gt_i32_e64 s[44:45], v67, v154
	s_and_b64 s[44:45], vcc, s[44:45]
	v_add_u32_e32 v67, 0xffffffa2, v197
	v_cndmask_b32_e64 v85, v66, v225, s[44:45]
	v_cmp_gt_i32_e64 s[44:45], v67, v154
	v_mul_f32_e32 v66, 0x3e38aa3b, v68
	s_and_b64 s[44:45], vcc, s[44:45]
	v_add_u32_e32 v67, 0xffffffa3, v197
	v_cndmask_b32_e64 v87, v66, v225, s[44:45]
	v_cmp_gt_i32_e64 s[44:45], v67, v154
	v_mul_f32_e32 v66, 0x3e38aa3b, v69
; DI int crow(int i, int hh) { return (i & 3) + 8 * (i >> 2) + 4 * hh; }
; DI float ex2(float x) { return __builtin_amdgcn_exp2f(x); }
; DI float xhalf_max(float v) { auto r = __builtin_amdgcn_permlane32_swap(__float_as_uint(v), __float_as_uint(v), false, false); return fmaxf(__uint_as_float(r[0]), __uint_as_float(r[1])); }
; template <int VSTR, bool DEFER = false>
; DI void softmax_pv(f32x16 (&st)[2], float& m, float& l, f32x16 (&o)[4], const char* vt, int erow0, int lane) {
;     ...
;   float mx = -1e30f;
; #pragma unroll
;   for (int mt = 0; mt < 2; ++mt)
; #pragma unroll
;     for (int i = 0; i < 16; ++i) mx = fmaxf(mx, st[mt][i]);
;   mx = xhalf_max(mx);
;   if (DEFER) {
;     constexpr float THR = 6.0f;
;     if (__any(mx > m + THR)) {
;       const float mn = fmaxf(m, mx);
;       const float al = ex2(m - mn);
;       m = mn;
;       l *= al;
; #pragma unroll
;       for (int et = 0; et < 4; ++et)
; #pragma unroll
;         for (int i = 0; i < 16; ++i) o[et][i] *= al;
;     }
; DI void phase_da_attn(const Params& p, int j, char* lds) {
;     ...
;         for (int mt = 0; mt < 2; ++mt)
; #pragma unroll
;           for (int i = 0; i < 16; ++i) {
;             float s = st[mt][i] * sc;
;             if (diag) { int key = kt * 64 + mt * 32 + crow(i, hh); if (key > myq) s = -1e30f; }
;             st[mt][i] = s;
;           }
	s_and_b64 s[44:45], vcc, s[44:45]
	v_add_u32_e32 v67, 0xffffffa8, v197
	v_cndmask_b32_e64 v90, v66, v225, s[44:45]
	v_cmp_gt_i32_e64 s[44:45], v67, v154
	v_mul_f32_e32 v66, 0x3e38aa3b, v70
	s_and_b64 s[44:45], vcc, s[44:45]
	v_add_u32_e32 v67, 0xffffffa9, v197
	v_cndmask_b32_e64 v86, v66, v225, s[44:45]
	v_cmp_gt_i32_e64 s[44:45], v67, v154
	v_mul_f32_e32 v66, 0x3e38aa3b, v71
	s_and_b64 s[44:45], vcc, s[44:45]
	v_add_u32_e32 v67, 0xffffffaa, v197
	v_cndmask_b32_e64 v88, v66, v225, s[44:45]
	v_cmp_gt_i32_e64 s[44:45], v67, v154
	v_mul_f32_e32 v66, 0x3e38aa3b, v72
	s_and_b64 s[44:45], vcc, s[44:45]
	v_add_u32_e32 v67, 0xffffffab, v197
	v_cndmask_b32_e64 v91, v66, v225, s[44:45]
	v_cmp_gt_i32_e64 s[44:45], v67, v154
	v_mul_f32_e32 v66, 0x3e38aa3b, v73
	s_and_b64 s[44:45], vcc, s[44:45]
	v_add_u32_e32 v67, 0xffffffb0, v197
	v_cndmask_b32_e64 v84, v66, v225, s[44:45]
	v_cmp_gt_i32_e64 s[44:45], v67, v154
	v_mul_f32_e32 v66, 0x3e38aa3b, v74
	s_and_b64 s[44:45], vcc, s[44:45]
	v_add_u32_e32 v67, 0xffffffb1, v197
	v_cndmask_b32_e64 v73, v66, v225, s[44:45]
	v_cmp_gt_i32_e64 s[44:45], v67, v154
	v_mul_f32_e32 v66, 0x3e38aa3b, v75
	s_and_b64 s[44:45], vcc, s[44:45]
	v_add_u32_e32 v67, 0xffffffb2, v197
	v_cndmask_b32_e64 v68, v66, v225, s[44:45]
	v_cmp_gt_i32_e64 s[44:45], v67, v154
	v_mul_f32_e32 v66, 0x3e38aa3b, v76
	s_and_b64 s[44:45], vcc, s[44:45]
	v_add_u32_e32 v67, 0xffffffb3, v197
	v_cndmask_b32_e64 v70, v66, v225, s[44:45]
	v_cmp_gt_i32_e64 s[44:45], v67, v154
	v_mul_f32_e32 v66, 0x3e38aa3b, v77
	s_and_b64 s[44:45], vcc, s[44:45]
	v_add_u32_e32 v67, 0xffffffb8, v197
	v_cndmask_b32_e64 v72, v66, v225, s[44:45]
	v_cmp_gt_i32_e64 s[44:45], v67, v154
	v_mul_f32_e32 v66, 0x3e38aa3b, v78
	s_and_b64 s[44:45], vcc, s[44:45]
	v_add_u32_e32 v69, 0xffffffb9, v197
	v_cndmask_b32_e64 v67, v66, v225, s[44:45]
	v_cmp_gt_i32_e64 s[44:45], v69, v154
	v_mul_f32_e32 v66, 0x3e38aa3b, v79
	s_and_b64 s[44:45], vcc, s[44:45]
	v_add_u32_e32 v71, 0xffffffba, v197
	v_cndmask_b32_e64 v69, v66, v225, s[44:45]
	v_cmp_gt_i32_e64 s[44:45], v71, v154
	v_mul_f32_e32 v66, 0x3e38aa3b, v80
	s_and_b64 s[44:45], vcc, s[44:45]
	v_add_u32_e32 v74, 0xffffffbb, v197
	v_cndmask_b32_e64 v71, v66, v225, s[44:45]
	v_cmp_gt_i32_e64 s[44:45], v74, v154
.Lda_max:
	v_max3_f32 v74, v82, s56, v83
	v_max3_f32 v74, v74, v155, v188
	v_max3_f32 v74, v74, v193, v194
	v_max3_f32 v74, v74, v195, v196
	v_max3_f32 v74, v74, v191, v192
	v_max3_f32 v74, v74, v189, v190
	v_max3_f32 v74, v74, v93, v94
	v_max3_f32 v74, v74, v95, v92
	v_max3_f32 v74, v74, v89, v85
	v_max3_f32 v74, v74, v87, v90
	v_max3_f32 v74, v74, v86, v88
	v_max3_f32 v74, v74, v91, v84
	v_max3_f32 v74, v74, v73, v68
	v_mul_f32_e32 v66, 0x3e38aa3b, v81
	s_and_b64 vcc, vcc, s[44:45]
	v_max3_f32 v74, v74, v70, v72
	v_cndmask_b32_e32 v66, v66, v225, vcc
	v_max3_f32 v74, v74, v67, v69
	v_max3_f32 v74, v74, v71, v66
	v_mov_b32_e32 v75, v74
	s_nop 1
	v_permlane32_swap_b32_e32 v74, v75
	v_max_f32_e32 v75, v75, v75
	v_max_f32_e32 v74, v74, v74
	v_max_f32_e32 v74, v74, v75
	v_add_f32_e32 v75, 0x40c00000, v149
	v_cmp_gt_f32_e32 vcc, v74, v75
	s_cbranch_vccz .LBB0_500
	v_max_f32_e32 v74, v74, v74
	v_max_f32_e32 v75, v149, v149
	v_max_f32_e32 v75, v75, v74
	v_sub_f32_e32 v74, v149, v75
	v_exp_f32_e32 v74, v74
	v_mov_b32_e32 v149, v75
	v_mul_f32_e32 v147, v147, v74
	v_pk_mul_f32 v[64:65], v[64:65], v[74:75] op_sel_hi:[1,0]
	v_pk_mul_f32 v[62:63], v[62:63], v[74:75] op_sel_hi:[1,0]
	v_pk_mul_f32 v[60:61], v[60:61], v[74:75] op_sel_hi:[1,0]
	v_pk_mul_f32 v[58:59], v[58:59], v[74:75] op_sel_hi:[1,0]
	v_pk_mul_f32 v[56:57], v[56:57], v[74:75] op_sel_hi:[1,0]
	v_pk_mul_f32 v[54:55], v[54:55], v[74:75] op_sel_hi:[1,0]
	v_pk_mul_f32 v[52:53], v[52:53], v[74:75] op_sel_hi:[1,0]
	v_pk_mul_f32 v[50:51], v[50:51], v[74:75] op_sel_hi:[1,0]
	v_pk_mul_f32 v[48:49], v[48:49], v[74:75] op_sel_hi:[1,0]
	v_pk_mul_f32 v[46:47], v[46:47], v[74:75] op_sel_hi:[1,0]
	v_pk_mul_f32 v[44:45], v[44:45], v[74:75] op_sel_hi:[1,0]
	v_pk_mul_f32 v[42:43], v[42:43], v[74:75] op_sel_hi:[1,0]
	v_pk_mul_f32 v[40:41], v[40:41], v[74:75] op_sel_hi:[1,0]
	v_pk_mul_f32 v[38:39], v[38:39], v[74:75] op_sel_hi:[1,0]
	v_pk_mul_f32 v[36:37], v[36:37], v[74:75] op_sel_hi:[1,0]
	v_pk_mul_f32 v[34:35], v[34:35], v[74:75] op_sel_hi:[1,0]
	v_pk_mul_f32 v[32:33], v[32:33], v[74:75] op_sel_hi:[1,0]
	v_pk_mul_f32 v[30:31], v[30:31], v[74:75] op_sel_hi:[1,0]
	v_pk_mul_f32 v[28:29], v[28:29], v[74:75] op_sel_hi:[1,0]
	v_pk_mul_f32 v[26:27], v[26:27], v[74:75] op_sel_hi:[1,0]
	v_pk_mul_f32 v[24:25], v[24:25], v[74:75] op_sel_hi:[1,0]
	v_pk_mul_f32 v[22:23], v[22:23], v[74:75] op_sel_hi:[1,0]
	v_pk_mul_f32 v[20:21], v[20:21], v[74:75] op_sel_hi:[1,0]
	v_pk_mul_f32 v[18:19], v[18:19], v[74:75] op_sel_hi:[1,0]
	v_pk_mul_f32 v[16:17], v[16:17], v[74:75] op_sel_hi:[1,0]
	v_pk_mul_f32 v[14:15], v[14:15], v[74:75] op_sel_hi:[1,0]
	v_pk_mul_f32 v[12:13], v[12:13], v[74:75] op_sel_hi:[1,0]
	v_pk_mul_f32 v[10:11], v[10:11], v[74:75] op_sel_hi:[1,0]
	v_pk_mul_f32 v[8:9], v[8:9], v[74:75] op_sel_hi:[1,0]
	v_pk_mul_f32 v[6:7], v[6:7], v[74:75] op_sel_hi:[1,0]
	v_pk_mul_f32 v[4:5], v[4:5], v[74:75] op_sel_hi:[1,0]
	v_pk_mul_f32 v[2:3], v[2:3], v[74:75] op_sel_hi:[1,0]

; DI int crow(int i, int hh) { return (i & 3) + 8 * (i >> 2) + 4 * hh; }
; DI f32x16 mfma(bf16x8 a, bf16x8 b, f32x16 c) { return __builtin_amdgcn_mfma_f32_32x32x16_bf16(a, b, c, 0, 0, 0); }
; DI f32x16 zero16() { f32x16 z; for (int i = 0; i < 16; ++i) z[i] = 0.f; return z; }
; DI void phase_da_attn(const Params& p, int j, char* lds) {
;     ...
;         f32x16 st[2];
; #pragma unroll
;         for (int mt = 0; mt < 2; ++mt) {
;           st[mt] = zero16();
;           const int row = mt * 32 + l31;
; #pragma unroll
;           for (int kk = 0; kk < 4; ++kk) {
;             int ch = c * 8 + kk * 2 + hh;
;             bf16x8 a = *(const bf16x8*)(kt_l + row * 256 + ((ch ^ (row & 15)) << 4));
;             st[mt] = mfma(a, qf[kk], st[mt]);
;           }
;         }
;         const bool diag = kt * 64 + 63 > q0;
; #pragma unroll
;         for (int mt = 0; mt < 2; ++mt)
; #pragma unroll
;           for (int i = 0; i < 16; ++i) {
;             float s = st[mt][i] * sc;
;             if (diag) { int key = kt * 64 + mt * 32 + crow(i, hh); if (key > myq) s = -1e30f; }
;             st[mt][i] = s;
;           }
.Lda_fast:
	v_add_u32_e32 v155, v70, v183
	v_add_u32_e32 v192, v70, v184
	v_add_u32_e32 v193, v70, v185
	ds_read_b128 v[226:229], v71
	ds_read_b128 v[230:233], v155
	ds_read_b128 v[234:237], v192
	ds_read_b128 v[238:241], v193
	ds_read_b128 v[242:245], v71 offset:8192
	ds_read_b128 v[246:249], v155 offset:8192
	ds_read_b128 v[188:191], v192 offset:8192
	ds_read_b128 v[194:197], v193 offset:8192
	s_waitcnt lgkmcnt(7)
	v_mfma_f32_32x32x16_bf16 v[82:97], v[226:229], v[110:113], 0
	s_waitcnt lgkmcnt(6)
	v_mfma_f32_32x32x16_bf16 v[82:97], v[230:233], v[106:109], v[82:97]
	s_waitcnt lgkmcnt(5)
	v_mfma_f32_32x32x16_bf16 v[82:97], v[234:237], v[102:105], v[82:97]
	s_waitcnt lgkmcnt(4)
	v_mfma_f32_32x32x16_bf16 v[82:97], v[238:241], v[98:101], v[82:97]
	s_waitcnt lgkmcnt(3)
	v_mfma_f32_32x32x16_bf16 v[66:81], v[242:245], v[110:113], 0
	s_waitcnt lgkmcnt(2)
	v_mfma_f32_32x32x16_bf16 v[66:81], v[246:249], v[106:109], v[66:81]
	s_waitcnt lgkmcnt(1)
	v_mfma_f32_32x32x16_bf16 v[66:81], v[188:191], v[102:105], v[66:81]
	s_waitcnt lgkmcnt(0)
	v_mfma_f32_32x32x16_bf16 v[66:81], v[194:197], v[98:101], v[66:81]
	s_nop 3
	v_mul_f32_e32 v82, 0x3e38aa3b, v82
	v_mul_f32_e32 v83, 0x3e38aa3b, v83
	v_mul_f32_e32 v155, 0x3e38aa3b, v84
	v_mul_f32_e32 v188, 0x3e38aa3b, v85
	v_mul_f32_e32 v193, 0x3e38aa3b, v86
	v_mul_f32_e32 v194, 0x3e38aa3b, v87
	v_mul_f32_e32 v195, 0x3e38aa3b, v88
	v_mul_f32_e32 v196, 0x3e38aa3b, v89
	v_mul_f32_e32 v191, 0x3e38aa3b, v90
	v_mul_f32_e32 v192, 0x3e38aa3b, v91
	v_mul_f32_e32 v189, 0x3e38aa3b, v92
	v_mul_f32_e32 v190, 0x3e38aa3b, v93
	v_mul_f32_e32 v93, 0x3e38aa3b, v94
	v_mul_f32_e32 v94, 0x3e38aa3b, v95
	v_mul_f32_e32 v95, 0x3e38aa3b, v96
	v_mul_f32_e32 v92, 0x3e38aa3b, v97
	v_mul_f32_e32 v89, 0x3e38aa3b, v66
	v_mul_f32_e32 v85, 0x3e38aa3b, v67
	v_mul_f32_e32 v87, 0x3e38aa3b, v68
	v_mul_f32_e32 v90, 0x3e38aa3b, v69
	v_mul_f32_e32 v86, 0x3e38aa3b, v70
	v_mul_f32_e32 v88, 0x3e38aa3b, v71
	v_mul_f32_e32 v91, 0x3e38aa3b, v72
	v_mul_f32_e32 v84, 0x3e38aa3b, v73
	v_mul_f32_e32 v73, 0x3e38aa3b, v74
	v_mul_f32_e32 v68, 0x3e38aa3b, v75
	v_mul_f32_e32 v70, 0x3e38aa3b, v76
	v_mul_f32_e32 v72, 0x3e38aa3b, v77
	v_mul_f32_e32 v67, 0x3e38aa3b, v78
	v_mul_f32_e32 v69, 0x3e38aa3b, v79
	v_mul_f32_e32 v71, 0x3e38aa3b, v80
	s_mov_b64 vcc, 0
	s_branch .Lda_max

; DI u64_t ag_ld64(u64_t* p) { return __hip_atomic_load(p, __ATOMIC_RELAXED, __HIP_MEMORY_SCOPE_AGENT); }
;   DI void operator()(f32x16 (&acc)[2][4], int grow0, int gcol0, int lane, int w, char* lds) {
;     ...
;     if (tid < 256) {
;       float s1 = 0.f, s2 = 0.f;
; #pragma unroll
;       for (int q = 0; q < 4; ++q) { u64_t v = ag_ld64(myslots + tid * 4 + q); s1 += __uint_as_float((unsigned)v); s2 += __uint_as_float((unsigned)(v >> 32)); }
;       float mean = s1 * (1.f / 1024.f); float var = s2 * (1.f / 1024.f) - mean * mean; var = var < 0.f ? 0.f : var;
;       f32x2 sv = {mean, rsqrtf(var + LN_EPS)}; *(f32x2*)(stat + tid * 2) = sv;
;     }
.LBB0_776:
	s_or_b64 exec, exec, s[6:7]
	s_barrier
	s_and_saveexec_b64 s[6:7], s[40:41]
	s_cbranch_execz .LBB0_778
	v_lshl_add_u64 v[64:65], v[168:169], 3, v[64:65]
	global_load_dword v168, v[64:65], off sc1
	global_load_dword v169, v[64:65], off offset:4 sc1
	global_load_dword v21, v[64:65], off offset:8 sc1
	global_load_dword v23, v[64:65], off offset:12 sc1
	global_load_dword v25, v[64:65], off offset:16 sc1
	global_load_dword v27, v[64:65], off offset:20 sc1
	global_load_dword v29, v[64:65], off offset:24 sc1
	global_load_dword v31, v[64:65], off offset:28 sc1
	s_mov_b32 s2, 0x3a800000
	s_waitcnt vmcnt(0)
	v_add_f32_e32 v0, 0, v168
	v_add_f32_e32 v19, 0, v169
	v_add_f32_e32 v0, v0, v21
	v_add_f32_e32 v19, v19, v23
	v_add_f32_e32 v0, v0, v25
	v_add_f32_e32 v19, v19, v27
	v_add_f32_e32 v0, v0, v29
	v_mul_f32_e32 v64, 0x3a800000, v0
	v_add_f32_e32 v19, v19, v31
	v_mul_f32_e32 v0, v64, v64
	v_fma_f32 v0, v19, s2, -v0
	v_cmp_ngt_f32_e32 vcc, 0, v0
	s_mov_b32 s2, 0x800000
	s_nop 0
	v_cndmask_b32_e32 v0, 0, v0, vcc
	v_add_f32_e32 v0, 0x3727c5ac, v0
	v_cmp_gt_f32_e32 vcc, s2, v0
	v_mul_f32_e32 v19, 0x4b800000, v0
	s_nop 0
	v_cndmask_b32_e32 v0, v0, v19, vcc
	v_rsq_f32_e32 v0, v0
	s_nop 0
	v_mul_f32_e32 v19, 0x45800000, v0
	v_cndmask_b32_e32 v65, v0, v19, vcc
	v_lshlrev_b32_e32 v0, 3, v163
	ds_write_b64 v0, v[64:65]
